# P1 specialised waves, norm rows 6 deep in flight instead of 4
# baseline (speedup 1.0000x reference)
.LBB0_441:
	s_waitcnt lgkmcnt(0)
	s_cmp_lt_u32 s69, 2
	s_cbranch_scc1 .LBB0_443
	v_mbcnt_lo_u32_b32 v65, -1, 0
	v_mbcnt_hi_u32_b32 v65, -1, v65
	v_lshlrev_b32_e32 v28, 3, v65
	v_lshlrev_b32_e32 v65, 4, v65
	v_mov_b32_e32 v64, 0x358637bd
	s_mov_b32 s22, 0x3a800000
	v_readlane_b32 s5, v254, 14
	v_readlane_b32 s2, v254, 8
	v_readlane_b32 s3, v254, 9
	s_mul_i32 s5, s5, 6
	s_add_i32 s5, s5, s69
	s_add_i32 s5, s5, -2
	s_cmp_lt_u32 s5, 64
	s_cselect_b32 s23, 0xc0000, 0
	s_cselect_b32 s28, 0x60000, 0
	s_lshl_b32 s4, s78, 24
	s_add_u32 s0, s12, s4
	s_addc_u32 s1, s13, 0
	s_lshl_b32 s4, s5, 12
	s_add_u32 s0, s0, s4
	s_addc_u32 s1, s1, 0
	s_add_u32 s2, s2, 0x4000000
	s_addc_u32 s3, s3, 0
	s_lshl_b32 s4, s78, 23
	s_add_u32 s2, s2, s4
	s_addc_u32 s3, s3, 0
	s_lshl_b32 s4, s5, 11
	s_add_u32 s2, s2, s4
	s_addc_u32 s3, s3, 0
	s_mul_i32 s4, s78, 0x12000
	s_add_u32 s8, s64, s4
	s_addc_u32 s9, s65, 0
	global_load_dwordx4 v[212:215], v65, s[8:9]
	global_load_dwordx4 v[216:219], v65, s[8:9] offset:1024
	global_load_dwordx4 v[220:223], v65, s[8:9] offset:2048
	global_load_dwordx4 v[224:227], v65, s[8:9] offset:3072
	s_add_u32 s8, s8, 0x1000
	s_addc_u32 s9, s9, 0
	global_load_dwordx4 v[194:197], v65, s[8:9]
	global_load_dwordx4 v[198:201], v65, s[8:9] offset:1024
	global_load_dwordx4 v[202:205], v65, s[8:9] offset:2048
	global_load_dwordx4 v[206:209], v65, s[8:9] offset:3072
	s_add_u32 s8, s8, 0x8000
	s_addc_u32 s9, s9, 0
	global_load_dwordx4 v[36:39], v65, s[8:9]
	global_load_dwordx4 v[40:43], v65, s[8:9] offset:1024
	global_load_dwordx4 v[44:47], v65, s[8:9] offset:2048
	global_load_dwordx4 v[48:51], v65, s[8:9] offset:3072
	s_add_u32 s8, s8, 0x1000
	s_addc_u32 s9, s9, 0
	global_load_dwordx4 v[228:231], v65, s[8:9]
	global_load_dwordx4 v[232:235], v65, s[8:9] offset:1024
	global_load_dwordx4 v[236:239], v65, s[8:9] offset:2048
	global_load_dwordx4 v[240:243], v65, s[8:9] offset:3072
	global_load_dwordx4 v[98:101], v65, s[0:1]
	global_load_dwordx4 v[102:105], v65, s[0:1] offset:1024
	global_load_dwordx4 v[106:109], v65, s[0:1] offset:2048
	global_load_dwordx4 v[110:113], v65, s[0:1] offset:3072
	s_add_u32 s0, s0, 0xc0000
	s_addc_u32 s1, s1, 0
	global_load_dwordx4 v[114:117], v65, s[0:1]
	global_load_dwordx4 v[118:121], v65, s[0:1] offset:1024
	global_load_dwordx4 v[122:125], v65, s[0:1] offset:2048
	global_load_dwordx4 v[126:129], v65, s[0:1] offset:3072
	s_add_u32 s0, s0, 0xc0000
	s_addc_u32 s1, s1, 0
	global_load_dwordx4 v[130:133], v65, s[0:1]
	global_load_dwordx4 v[134:137], v65, s[0:1] offset:1024
	global_load_dwordx4 v[138:141], v65, s[0:1] offset:2048
	global_load_dwordx4 v[142:145], v65, s[0:1] offset:3072
	s_add_u32 s0, s0, 0xc0000
	s_addc_u32 s1, s1, 0
	global_load_dwordx4 v[146:149], v65, s[0:1]
	global_load_dwordx4 v[150:153], v65, s[0:1] offset:1024
	global_load_dwordx4 v[154:157], v65, s[0:1] offset:2048
	global_load_dwordx4 v[158:161], v65, s[0:1] offset:3072
	s_add_u32 s0, s0, 0xc0000
	s_addc_u32 s1, s1, 0
	global_load_dwordx4 v[162:165], v65, s[0:1]
	global_load_dwordx4 v[166:169], v65, s[0:1] offset:1024
	global_load_dwordx4 v[170:173], v65, s[0:1] offset:2048
	global_load_dwordx4 v[174:177], v65, s[0:1] offset:3072
	s_add_u32 s0, s0, 0xc0000
	s_addc_u32 s1, s1, 0
	global_load_dwordx4 v[178:181], v65, s[0:1]
	global_load_dwordx4 v[182:185], v65, s[0:1] offset:1024
	global_load_dwordx4 v[186:189], v65, s[0:1] offset:2048
	global_load_dwordx4 v[190:193], v65, s[0:1] offset:3072
	s_add_u32 s0, s0, 0xc0000
	s_addc_u32 s1, s1, 0
	s_waitcnt vmcnt(16)
	v_mul_f32_e32 v52, v98, v98
	v_mul_f32_e32 v53, v102, v102
	v_mul_f32_e32 v54, v106, v106
	v_mul_f32_e32 v55, v110, v110
	v_mul_f32_e32 v56, v114, v114
	v_mul_f32_e32 v57, v118, v118
	v_mul_f32_e32 v58, v122, v122
	v_mul_f32_e32 v59, v126, v126
	v_fmac_f32_e32 v52, v99, v99
	v_fmac_f32_e32 v53, v103, v103
	v_fmac_f32_e32 v54, v107, v107
	v_fmac_f32_e32 v55, v111, v111
	v_fmac_f32_e32 v56, v115, v115
	v_fmac_f32_e32 v57, v119, v119
	v_fmac_f32_e32 v58, v123, v123
	v_fmac_f32_e32 v59, v127, v127
	v_fmac_f32_e32 v52, v100, v100
	v_fmac_f32_e32 v53, v104, v104
	v_fmac_f32_e32 v54, v108, v108
	v_fmac_f32_e32 v55, v112, v112
	v_fmac_f32_e32 v56, v116, v116
	v_fmac_f32_e32 v57, v120, v120
	v_fmac_f32_e32 v58, v124, v124
	v_fmac_f32_e32 v59, v128, v128
	v_fmac_f32_e32 v52, v101, v101
	v_fmac_f32_e32 v53, v105, v105
	v_fmac_f32_e32 v54, v109, v109
	v_fmac_f32_e32 v55, v113, v113
	v_fmac_f32_e32 v56, v117, v117
	v_fmac_f32_e32 v57, v121, v121
	v_fmac_f32_e32 v58, v125, v125
	v_fmac_f32_e32 v59, v129, v129
	v_add_f32_e32 v52, v52, v53
	v_add_f32_e32 v54, v54, v55
	v_add_f32_e32 v56, v56, v57
	v_add_f32_e32 v58, v58, v59
	v_add_f32_e32 v60, v52, v54
	v_add_f32_e32 v61, v56, v58
	s_nop 0
	v_add_f32_dpp v60, v60, v60 quad_perm:[1,0,3,2] row_mask:0xf bank_mask:0xf
	v_add_f32_dpp v61, v61, v61 quad_perm:[1,0,3,2] row_mask:0xf bank_mask:0xf
	s_nop 0
	v_add_f32_dpp v60, v60, v60 quad_perm:[2,3,0,1] row_mask:0xf bank_mask:0xf
	v_add_f32_dpp v61, v61, v61 quad_perm:[2,3,0,1] row_mask:0xf bank_mask:0xf
	s_nop 0
	v_add_f32_dpp v60, v60, v60 row_half_mirror row_mask:0xf bank_mask:0xf
	v_add_f32_dpp v61, v61, v61 row_half_mirror row_mask:0xf bank_mask:0xf
	s_nop 0
	v_add_f32_dpp v60, v60, v60 row_mirror row_mask:0xf bank_mask:0xf
	v_add_f32_dpp v61, v61, v61 row_mirror row_mask:0xf bank_mask:0xf
	s_nop 0
	v_add_f32_dpp v60, v60, v60 row_bcast:15 row_mask:0xa bank_mask:0xf
	v_add_f32_dpp v61, v61, v61 row_bcast:15 row_mask:0xa bank_mask:0xf
	s_nop 0
	v_add_f32_dpp v60, v60, v60 row_bcast:31 row_mask:0xc bank_mask:0xf
	v_add_f32_dpp v61, v61, v61 row_bcast:31 row_mask:0xc bank_mask:0xf
	s_nop 0
	v_fma_f32 v60, v60, s22, v64
	v_fma_f32 v61, v61, s22, v64
	v_rsq_f32_e32 v60, v60
	v_rsq_f32_e32 v61, v61
	s_nop 0
	v_readlane_b32 s10, v60, 63
	v_readlane_b32 s11, v61, 63
	s_nop 1
	v_mul_f32_e32 v62, s10, v98
	v_fma_f32 v98, v62, v194, v212
	v_mul_f32_e32 v63, s10, v99
	v_fma_f32 v99, v63, v195, v213
	v_mul_f32_e32 v62, s10, v100
	v_fma_f32 v100, v62, v196, v214
	v_mul_f32_e32 v63, s10, v101
	v_fma_f32 v101, v63, v197, v215
	v_mul_f32_e32 v62, s10, v102
	v_fma_f32 v102, v62, v198, v216
	v_mul_f32_e32 v63, s10, v103
	v_fma_f32 v103, v63, v199, v217
	v_mul_f32_e32 v62, s10, v104
	v_fma_f32 v104, v62, v200, v218
	v_mul_f32_e32 v63, s10, v105
	v_fma_f32 v105, v63, v201, v219
	v_mul_f32_e32 v62, s10, v106
	v_fma_f32 v106, v62, v202, v220
	v_mul_f32_e32 v63, s10, v107
	v_fma_f32 v107, v63, v203, v221
	v_mul_f32_e32 v62, s10, v108
	v_fma_f32 v108, v62, v204, v222
	v_mul_f32_e32 v63, s10, v109
	v_fma_f32 v109, v63, v205, v223
	v_mul_f32_e32 v62, s10, v110
	v_fma_f32 v110, v62, v206, v224
	v_mul_f32_e32 v63, s10, v111
	v_fma_f32 v111, v63, v207, v225
	v_mul_f32_e32 v62, s10, v112
	v_fma_f32 v112, v62, v208, v226
	v_mul_f32_e32 v63, s10, v113
	v_fma_f32 v113, v63, v209, v227
	v_cvt_pk_bf16_f32 v244, v98, v99
	v_cvt_pk_bf16_f32 v245, v100, v101
	v_cvt_pk_bf16_f32 v246, v102, v103
	v_cvt_pk_bf16_f32 v247, v104, v105
	v_cvt_pk_bf16_f32 v248, v106, v107
	v_cvt_pk_bf16_f32 v249, v108, v109
	v_cvt_pk_bf16_f32 v250, v110, v111
	v_cvt_pk_bf16_f32 v251, v112, v113
	global_store_dwordx2 v28, v[244:245], s[2:3]
	global_store_dwordx2 v28, v[246:247], s[2:3] offset:512
	global_store_dwordx2 v28, v[248:249], s[2:3] offset:1024
	global_store_dwordx2 v28, v[250:251], s[2:3] offset:1536
	s_add_u32 s2, s2, 0x60000
	s_addc_u32 s3, s3, 0
	v_mul_f32_e32 v62, s11, v114
	v_fma_f32 v114, v62, v194, v212
	v_mul_f32_e32 v63, s11, v115
	v_fma_f32 v115, v63, v195, v213
	v_mul_f32_e32 v62, s11, v116
	v_fma_f32 v116, v62, v196, v214
	v_mul_f32_e32 v63, s11, v117
	v_fma_f32 v117, v63, v197, v215
	v_mul_f32_e32 v62, s11, v118
	v_fma_f32 v118, v62, v198, v216
	v_mul_f32_e32 v63, s11, v119
	v_fma_f32 v119, v63, v199, v217
	v_mul_f32_e32 v62, s11, v120
	v_fma_f32 v120, v62, v200, v218
	v_mul_f32_e32 v63, s11, v121
	v_fma_f32 v121, v63, v201, v219
	v_mul_f32_e32 v62, s11, v122
	v_fma_f32 v122, v62, v202, v220
	v_mul_f32_e32 v63, s11, v123
	v_fma_f32 v123, v63, v203, v221
	v_mul_f32_e32 v62, s11, v124
	v_fma_f32 v124, v62, v204, v222
	v_mul_f32_e32 v63, s11, v125
	v_fma_f32 v125, v63, v205, v223
	v_mul_f32_e32 v62, s11, v126
	v_fma_f32 v126, v62, v206, v224
	v_mul_f32_e32 v63, s11, v127
	v_fma_f32 v127, v63, v207, v225
	v_mul_f32_e32 v62, s11, v128
	v_fma_f32 v128, v62, v208, v226
	v_mul_f32_e32 v63, s11, v129
	v_fma_f32 v129, v63, v209, v227
	v_cvt_pk_bf16_f32 v10, v114, v115
	v_cvt_pk_bf16_f32 v11, v116, v117
	v_cvt_pk_bf16_f32 v12, v118, v119
	v_cvt_pk_bf16_f32 v13, v120, v121
	v_cvt_pk_bf16_f32 v14, v122, v123
	v_cvt_pk_bf16_f32 v15, v124, v125
	v_cvt_pk_bf16_f32 v16, v126, v127
	v_cvt_pk_bf16_f32 v17, v128, v129
	global_store_dwordx2 v28, v[10:11], s[2:3]
	global_store_dwordx2 v28, v[12:13], s[2:3] offset:512
	global_store_dwordx2 v28, v[14:15], s[2:3] offset:1024
	global_store_dwordx2 v28, v[16:17], s[2:3] offset:1536
	s_add_u32 s2, s2, 0x60000
	s_addc_u32 s3, s3, 0
	global_load_dwordx4 v[98:101], v65, s[0:1]
	global_load_dwordx4 v[102:105], v65, s[0:1] offset:1024
	global_load_dwordx4 v[106:109], v65, s[0:1] offset:2048
	global_load_dwordx4 v[110:113], v65, s[0:1] offset:3072
	s_add_u32 s0, s0, 0xc0000
	s_addc_u32 s1, s1, 0
	global_load_dwordx4 v[114:117], v65, s[0:1]
	global_load_dwordx4 v[118:121], v65, s[0:1] offset:1024
	global_load_dwordx4 v[122:125], v65, s[0:1] offset:2048
	global_load_dwordx4 v[126:129], v65, s[0:1] offset:3072
	s_add_u32 s0, s0, 0xc0000
	s_addc_u32 s1, s1, 0
	s_waitcnt vmcnt(24)
	v_mul_f32_e32 v52, v130, v130
	v_mul_f32_e32 v53, v134, v134
	v_mul_f32_e32 v54, v138, v138
	v_mul_f32_e32 v55, v142, v142
	v_mul_f32_e32 v56, v146, v146
	v_mul_f32_e32 v57, v150, v150
	v_mul_f32_e32 v58, v154, v154
	v_mul_f32_e32 v59, v158, v158
	v_fmac_f32_e32 v52, v131, v131
	v_fmac_f32_e32 v53, v135, v135
	v_fmac_f32_e32 v54, v139, v139
	v_fmac_f32_e32 v55, v143, v143
	v_fmac_f32_e32 v56, v147, v147
	v_fmac_f32_e32 v57, v151, v151
	v_fmac_f32_e32 v58, v155, v155
	v_fmac_f32_e32 v59, v159, v159
	v_fmac_f32_e32 v52, v132, v132
	v_fmac_f32_e32 v53, v136, v136
	v_fmac_f32_e32 v54, v140, v140
	v_fmac_f32_e32 v55, v144, v144
	v_fmac_f32_e32 v56, v148, v148
	v_fmac_f32_e32 v57, v152, v152
	v_fmac_f32_e32 v58, v156, v156
	v_fmac_f32_e32 v59, v160, v160
	v_fmac_f32_e32 v52, v133, v133
	v_fmac_f32_e32 v53, v137, v137
	v_fmac_f32_e32 v54, v141, v141
	v_fmac_f32_e32 v55, v145, v145
	v_fmac_f32_e32 v56, v149, v149
	v_fmac_f32_e32 v57, v153, v153
	v_fmac_f32_e32 v58, v157, v157
	v_fmac_f32_e32 v59, v161, v161
	v_add_f32_e32 v52, v52, v53
	v_add_f32_e32 v54, v54, v55
	v_add_f32_e32 v56, v56, v57
	v_add_f32_e32 v58, v58, v59
	v_add_f32_e32 v60, v52, v54
	v_add_f32_e32 v61, v56, v58
	s_nop 0
	v_add_f32_dpp v60, v60, v60 quad_perm:[1,0,3,2] row_mask:0xf bank_mask:0xf
	v_add_f32_dpp v61, v61, v61 quad_perm:[1,0,3,2] row_mask:0xf bank_mask:0xf
	s_nop 0
	v_add_f32_dpp v60, v60, v60 quad_perm:[2,3,0,1] row_mask:0xf bank_mask:0xf
	v_add_f32_dpp v61, v61, v61 quad_perm:[2,3,0,1] row_mask:0xf bank_mask:0xf
	s_nop 0
	v_add_f32_dpp v60, v60, v60 row_half_mirror row_mask:0xf bank_mask:0xf
	v_add_f32_dpp v61, v61, v61 row_half_mirror row_mask:0xf bank_mask:0xf
	s_nop 0
	v_add_f32_dpp v60, v60, v60 row_mirror row_mask:0xf bank_mask:0xf
	v_add_f32_dpp v61, v61, v61 row_mirror row_mask:0xf bank_mask:0xf
	s_nop 0
	v_add_f32_dpp v60, v60, v60 row_bcast:15 row_mask:0xa bank_mask:0xf
	v_add_f32_dpp v61, v61, v61 row_bcast:15 row_mask:0xa bank_mask:0xf
	s_nop 0
	v_add_f32_dpp v60, v60, v60 row_bcast:31 row_mask:0xc bank_mask:0xf
	v_add_f32_dpp v61, v61, v61 row_bcast:31 row_mask:0xc bank_mask:0xf
	s_nop 0
	v_fma_f32 v60, v60, s22, v64
	v_fma_f32 v61, v61, s22, v64
	v_rsq_f32_e32 v60, v60
	v_rsq_f32_e32 v61, v61
	s_nop 0
	v_readlane_b32 s10, v60, 63
	v_readlane_b32 s11, v61, 63
	s_nop 1
	v_mul_f32_e32 v62, s10, v130
	v_fma_f32 v130, v62, v194, v212
	v_mul_f32_e32 v63, s10, v131
	v_fma_f32 v131, v63, v195, v213
	v_mul_f32_e32 v62, s10, v132
	v_fma_f32 v132, v62, v196, v214
	v_mul_f32_e32 v63, s10, v133
	v_fma_f32 v133, v63, v197, v215
	v_mul_f32_e32 v62, s10, v134
	v_fma_f32 v134, v62, v198, v216
	v_mul_f32_e32 v63, s10, v135
	v_fma_f32 v135, v63, v199, v217
	v_mul_f32_e32 v62, s10, v136
	v_fma_f32 v136, v62, v200, v218
	v_mul_f32_e32 v63, s10, v137
	v_fma_f32 v137, v63, v201, v219
	v_mul_f32_e32 v62, s10, v138
	v_fma_f32 v138, v62, v202, v220
	v_mul_f32_e32 v63, s10, v139
	v_fma_f32 v139, v63, v203, v221
	v_mul_f32_e32 v62, s10, v140
	v_fma_f32 v140, v62, v204, v222
	v_mul_f32_e32 v63, s10, v141
	v_fma_f32 v141, v63, v205, v223
	v_mul_f32_e32 v62, s10, v142
	v_fma_f32 v142, v62, v206, v224
	v_mul_f32_e32 v63, s10, v143
	v_fma_f32 v143, v63, v207, v225
	v_mul_f32_e32 v62, s10, v144
	v_fma_f32 v144, v62, v208, v226
	v_mul_f32_e32 v63, s10, v145
	v_fma_f32 v145, v63, v209, v227
	v_cvt_pk_bf16_f32 v244, v130, v131
	v_cvt_pk_bf16_f32 v245, v132, v133
	v_cvt_pk_bf16_f32 v246, v134, v135
	v_cvt_pk_bf16_f32 v247, v136, v137
	v_cvt_pk_bf16_f32 v248, v138, v139
	v_cvt_pk_bf16_f32 v249, v140, v141
	v_cvt_pk_bf16_f32 v250, v142, v143
	v_cvt_pk_bf16_f32 v251, v144, v145
	global_store_dwordx2 v28, v[244:245], s[2:3]
	global_store_dwordx2 v28, v[246:247], s[2:3] offset:512
	global_store_dwordx2 v28, v[248:249], s[2:3] offset:1024
	global_store_dwordx2 v28, v[250:251], s[2:3] offset:1536
	s_add_u32 s2, s2, 0x60000
	s_addc_u32 s3, s3, 0
	v_mul_f32_e32 v62, s11, v146
	v_fma_f32 v146, v62, v194, v212
	v_mul_f32_e32 v63, s11, v147
	v_fma_f32 v147, v63, v195, v213
	v_mul_f32_e32 v62, s11, v148
	v_fma_f32 v148, v62, v196, v214
	v_mul_f32_e32 v63, s11, v149
	v_fma_f32 v149, v63, v197, v215
	v_mul_f32_e32 v62, s11, v150
	v_fma_f32 v150, v62, v198, v216
	v_mul_f32_e32 v63, s11, v151
	v_fma_f32 v151, v63, v199, v217
	v_mul_f32_e32 v62, s11, v152
	v_fma_f32 v152, v62, v200, v218
	v_mul_f32_e32 v63, s11, v153
	v_fma_f32 v153, v63, v201, v219
	v_mul_f32_e32 v62, s11, v154
	v_fma_f32 v154, v62, v202, v220
	v_mul_f32_e32 v63, s11, v155
	v_fma_f32 v155, v63, v203, v221
	v_mul_f32_e32 v62, s11, v156
	v_fma_f32 v156, v62, v204, v222
	v_mul_f32_e32 v63, s11, v157
	v_fma_f32 v157, v63, v205, v223
	v_mul_f32_e32 v62, s11, v158
	v_fma_f32 v158, v62, v206, v224
	v_mul_f32_e32 v63, s11, v159
	v_fma_f32 v159, v63, v207, v225
	v_mul_f32_e32 v62, s11, v160
	v_fma_f32 v160, v62, v208, v226
	v_mul_f32_e32 v63, s11, v161
	v_fma_f32 v161, v63, v209, v227
	v_cvt_pk_bf16_f32 v10, v146, v147
	v_cvt_pk_bf16_f32 v11, v148, v149
	v_cvt_pk_bf16_f32 v12, v150, v151
	v_cvt_pk_bf16_f32 v13, v152, v153
	v_cvt_pk_bf16_f32 v14, v154, v155
	v_cvt_pk_bf16_f32 v15, v156, v157
	v_cvt_pk_bf16_f32 v16, v158, v159
	v_cvt_pk_bf16_f32 v17, v160, v161
	global_store_dwordx2 v28, v[10:11], s[2:3]
	global_store_dwordx2 v28, v[12:13], s[2:3] offset:512
	global_store_dwordx2 v28, v[14:15], s[2:3] offset:1024
	global_store_dwordx2 v28, v[16:17], s[2:3] offset:1536
	s_add_u32 s2, s2, 0x60000
	s_addc_u32 s3, s3, 0
	global_load_dwordx4 v[130:133], v65, s[0:1]
	global_load_dwordx4 v[134:137], v65, s[0:1] offset:1024
	global_load_dwordx4 v[138:141], v65, s[0:1] offset:2048
	global_load_dwordx4 v[142:145], v65, s[0:1] offset:3072
	s_add_u32 s0, s0, 0xc0000
	s_addc_u32 s1, s1, 0
	global_load_dwordx4 v[146:149], v65, s[0:1]
	global_load_dwordx4 v[150:153], v65, s[0:1] offset:1024
	global_load_dwordx4 v[154:157], v65, s[0:1] offset:2048
	global_load_dwordx4 v[158:161], v65, s[0:1] offset:3072
	s_add_u32 s0, s0, 0xc0000
	s_addc_u32 s1, s1, 0
	s_waitcnt vmcnt(32)
	v_mul_f32_e32 v52, v162, v162
	v_mul_f32_e32 v53, v166, v166
	v_mul_f32_e32 v54, v170, v170
	v_mul_f32_e32 v55, v174, v174
	v_mul_f32_e32 v56, v178, v178
	v_mul_f32_e32 v57, v182, v182
	v_mul_f32_e32 v58, v186, v186
	v_mul_f32_e32 v59, v190, v190
	v_fmac_f32_e32 v52, v163, v163
	v_fmac_f32_e32 v53, v167, v167
	v_fmac_f32_e32 v54, v171, v171
	v_fmac_f32_e32 v55, v175, v175
	v_fmac_f32_e32 v56, v179, v179
	v_fmac_f32_e32 v57, v183, v183
	v_fmac_f32_e32 v58, v187, v187
	v_fmac_f32_e32 v59, v191, v191
	v_fmac_f32_e32 v52, v164, v164
	v_fmac_f32_e32 v53, v168, v168
	v_fmac_f32_e32 v54, v172, v172
	v_fmac_f32_e32 v55, v176, v176
	v_fmac_f32_e32 v56, v180, v180
	v_fmac_f32_e32 v57, v184, v184
	v_fmac_f32_e32 v58, v188, v188
	v_fmac_f32_e32 v59, v192, v192
	v_fmac_f32_e32 v52, v165, v165
	v_fmac_f32_e32 v53, v169, v169
	v_fmac_f32_e32 v54, v173, v173
	v_fmac_f32_e32 v55, v177, v177
	v_fmac_f32_e32 v56, v181, v181
	v_fmac_f32_e32 v57, v185, v185
	v_fmac_f32_e32 v58, v189, v189
	v_fmac_f32_e32 v59, v193, v193
	v_add_f32_e32 v52, v52, v53
	v_add_f32_e32 v54, v54, v55
	v_add_f32_e32 v56, v56, v57
	v_add_f32_e32 v58, v58, v59
	v_add_f32_e32 v60, v52, v54
	v_add_f32_e32 v61, v56, v58
	s_nop 0
	v_add_f32_dpp v60, v60, v60 quad_perm:[1,0,3,2] row_mask:0xf bank_mask:0xf
	v_add_f32_dpp v61, v61, v61 quad_perm:[1,0,3,2] row_mask:0xf bank_mask:0xf
	s_nop 0
	v_add_f32_dpp v60, v60, v60 quad_perm:[2,3,0,1] row_mask:0xf bank_mask:0xf
	v_add_f32_dpp v61, v61, v61 quad_perm:[2,3,0,1] row_mask:0xf bank_mask:0xf
	s_nop 0
	v_add_f32_dpp v60, v60, v60 row_half_mirror row_mask:0xf bank_mask:0xf
	v_add_f32_dpp v61, v61, v61 row_half_mirror row_mask:0xf bank_mask:0xf
	s_nop 0
	v_add_f32_dpp v60, v60, v60 row_mirror row_mask:0xf bank_mask:0xf
	v_add_f32_dpp v61, v61, v61 row_mirror row_mask:0xf bank_mask:0xf
	s_nop 0
	v_add_f32_dpp v60, v60, v60 row_bcast:15 row_mask:0xa bank_mask:0xf
	v_add_f32_dpp v61, v61, v61 row_bcast:15 row_mask:0xa bank_mask:0xf
	s_nop 0
	v_add_f32_dpp v60, v60, v60 row_bcast:31 row_mask:0xc bank_mask:0xf
	v_add_f32_dpp v61, v61, v61 row_bcast:31 row_mask:0xc bank_mask:0xf
	s_nop 0
	v_fma_f32 v60, v60, s22, v64
	v_fma_f32 v61, v61, s22, v64
	v_rsq_f32_e32 v60, v60
	v_rsq_f32_e32 v61, v61
	s_nop 0
	v_readlane_b32 s10, v60, 63
	v_readlane_b32 s11, v61, 63
	s_nop 1
	v_mul_f32_e32 v62, s10, v162
	v_fma_f32 v162, v62, v194, v212
	v_mul_f32_e32 v63, s10, v163
	v_fma_f32 v163, v63, v195, v213
	v_mul_f32_e32 v62, s10, v164
	v_fma_f32 v164, v62, v196, v214
	v_mul_f32_e32 v63, s10, v165
	v_fma_f32 v165, v63, v197, v215
	v_mul_f32_e32 v62, s10, v166
	v_fma_f32 v166, v62, v198, v216
	v_mul_f32_e32 v63, s10, v167
	v_fma_f32 v167, v63, v199, v217
	v_mul_f32_e32 v62, s10, v168
	v_fma_f32 v168, v62, v200, v218
	v_mul_f32_e32 v63, s10, v169
	v_fma_f32 v169, v63, v201, v219
	v_mul_f32_e32 v62, s10, v170
	v_fma_f32 v170, v62, v202, v220
	v_mul_f32_e32 v63, s10, v171
	v_fma_f32 v171, v63, v203, v221
	v_mul_f32_e32 v62, s10, v172
	v_fma_f32 v172, v62, v204, v222
	v_mul_f32_e32 v63, s10, v173
	v_fma_f32 v173, v63, v205, v223
	v_mul_f32_e32 v62, s10, v174
	v_fma_f32 v174, v62, v206, v224
	v_mul_f32_e32 v63, s10, v175
	v_fma_f32 v175, v63, v207, v225
	v_mul_f32_e32 v62, s10, v176
	v_fma_f32 v176, v62, v208, v226
	v_mul_f32_e32 v63, s10, v177
	v_fma_f32 v177, v63, v209, v227
	v_cvt_pk_bf16_f32 v244, v162, v163
	v_cvt_pk_bf16_f32 v245, v164, v165
	v_cvt_pk_bf16_f32 v246, v166, v167
	v_cvt_pk_bf16_f32 v247, v168, v169
	v_cvt_pk_bf16_f32 v248, v170, v171
	v_cvt_pk_bf16_f32 v249, v172, v173
	v_cvt_pk_bf16_f32 v250, v174, v175
	v_cvt_pk_bf16_f32 v251, v176, v177
	global_store_dwordx2 v28, v[244:245], s[2:3]
	global_store_dwordx2 v28, v[246:247], s[2:3] offset:512
	global_store_dwordx2 v28, v[248:249], s[2:3] offset:1024
	global_store_dwordx2 v28, v[250:251], s[2:3] offset:1536
	s_add_u32 s2, s2, 0x60000
	s_addc_u32 s3, s3, 0
	v_mul_f32_e32 v62, s11, v178
	v_fma_f32 v178, v62, v194, v212
	v_mul_f32_e32 v63, s11, v179
	v_fma_f32 v179, v63, v195, v213
	v_mul_f32_e32 v62, s11, v180
	v_fma_f32 v180, v62, v196, v214
	v_mul_f32_e32 v63, s11, v181
	v_fma_f32 v181, v63, v197, v215
	v_mul_f32_e32 v62, s11, v182
	v_fma_f32 v182, v62, v198, v216
	v_mul_f32_e32 v63, s11, v183
	v_fma_f32 v183, v63, v199, v217
	v_mul_f32_e32 v62, s11, v184
	v_fma_f32 v184, v62, v200, v218
	v_mul_f32_e32 v63, s11, v185
	v_fma_f32 v185, v63, v201, v219
	v_mul_f32_e32 v62, s11, v186
	v_fma_f32 v186, v62, v202, v220
	v_mul_f32_e32 v63, s11, v187
	v_fma_f32 v187, v63, v203, v221
	v_mul_f32_e32 v62, s11, v188
	v_fma_f32 v188, v62, v204, v222
	v_mul_f32_e32 v63, s11, v189
	v_fma_f32 v189, v63, v205, v223
	v_mul_f32_e32 v62, s11, v190
	v_fma_f32 v190, v62, v206, v224
	v_mul_f32_e32 v63, s11, v191
	v_fma_f32 v191, v63, v207, v225
	v_mul_f32_e32 v62, s11, v192
	v_fma_f32 v192, v62, v208, v226
	v_mul_f32_e32 v63, s11, v193
	v_fma_f32 v193, v63, v209, v227
	v_cvt_pk_bf16_f32 v10, v178, v179
	v_cvt_pk_bf16_f32 v11, v180, v181
	v_cvt_pk_bf16_f32 v12, v182, v183
	v_cvt_pk_bf16_f32 v13, v184, v185
	v_cvt_pk_bf16_f32 v14, v186, v187
	v_cvt_pk_bf16_f32 v15, v188, v189
	v_cvt_pk_bf16_f32 v16, v190, v191
	v_cvt_pk_bf16_f32 v17, v192, v193
	global_store_dwordx2 v28, v[10:11], s[2:3]
	global_store_dwordx2 v28, v[12:13], s[2:3] offset:512
	global_store_dwordx2 v28, v[14:15], s[2:3] offset:1024
	global_store_dwordx2 v28, v[16:17], s[2:3] offset:1536
	s_add_u32 s2, s2, 0x60000
	s_addc_u32 s3, s3, 0
	global_load_dwordx4 v[162:165], v65, s[0:1]
	global_load_dwordx4 v[166:169], v65, s[0:1] offset:1024
	global_load_dwordx4 v[170:173], v65, s[0:1] offset:2048
	global_load_dwordx4 v[174:177], v65, s[0:1] offset:3072
	s_add_u32 s0, s0, 0xc0000
	s_addc_u32 s1, s1, 0
	global_load_dwordx4 v[178:181], v65, s[0:1]
	global_load_dwordx4 v[182:185], v65, s[0:1] offset:1024
	global_load_dwordx4 v[186:189], v65, s[0:1] offset:2048
	global_load_dwordx4 v[190:193], v65, s[0:1] offset:3072
	s_add_u32 s0, s0, 0xc0000
	s_addc_u32 s1, s1, 0
	s_waitcnt vmcnt(32)
	v_mul_f32_e32 v52, v98, v98
	v_mul_f32_e32 v53, v102, v102
	v_mul_f32_e32 v54, v106, v106
	v_mul_f32_e32 v55, v110, v110
	v_mul_f32_e32 v56, v114, v114
	v_mul_f32_e32 v57, v118, v118
	v_mul_f32_e32 v58, v122, v122
	v_mul_f32_e32 v59, v126, v126
	v_fmac_f32_e32 v52, v99, v99
	v_fmac_f32_e32 v53, v103, v103
	v_fmac_f32_e32 v54, v107, v107
	v_fmac_f32_e32 v55, v111, v111
	v_fmac_f32_e32 v56, v115, v115
	v_fmac_f32_e32 v57, v119, v119
	v_fmac_f32_e32 v58, v123, v123
	v_fmac_f32_e32 v59, v127, v127
	v_fmac_f32_e32 v52, v100, v100
	v_fmac_f32_e32 v53, v104, v104
	v_fmac_f32_e32 v54, v108, v108
	v_fmac_f32_e32 v55, v112, v112
	v_fmac_f32_e32 v56, v116, v116
	v_fmac_f32_e32 v57, v120, v120
	v_fmac_f32_e32 v58, v124, v124
	v_fmac_f32_e32 v59, v128, v128
	v_fmac_f32_e32 v52, v101, v101
	v_fmac_f32_e32 v53, v105, v105
	v_fmac_f32_e32 v54, v109, v109
	v_fmac_f32_e32 v55, v113, v113
	v_fmac_f32_e32 v56, v117, v117
	v_fmac_f32_e32 v57, v121, v121
	v_fmac_f32_e32 v58, v125, v125
	v_fmac_f32_e32 v59, v129, v129
	v_add_f32_e32 v52, v52, v53
	v_add_f32_e32 v54, v54, v55
	v_add_f32_e32 v56, v56, v57
	v_add_f32_e32 v58, v58, v59
	v_add_f32_e32 v60, v52, v54
	v_add_f32_e32 v61, v56, v58
	s_nop 0
	v_add_f32_dpp v60, v60, v60 quad_perm:[1,0,3,2] row_mask:0xf bank_mask:0xf
	v_add_f32_dpp v61, v61, v61 quad_perm:[1,0,3,2] row_mask:0xf bank_mask:0xf
	s_nop 0
	v_add_f32_dpp v60, v60, v60 quad_perm:[2,3,0,1] row_mask:0xf bank_mask:0xf
	v_add_f32_dpp v61, v61, v61 quad_perm:[2,3,0,1] row_mask:0xf bank_mask:0xf
	s_nop 0
	v_add_f32_dpp v60, v60, v60 row_half_mirror row_mask:0xf bank_mask:0xf
	v_add_f32_dpp v61, v61, v61 row_half_mirror row_mask:0xf bank_mask:0xf
	s_nop 0
	v_add_f32_dpp v60, v60, v60 row_mirror row_mask:0xf bank_mask:0xf
	v_add_f32_dpp v61, v61, v61 row_mirror row_mask:0xf bank_mask:0xf
	s_nop 0
	v_add_f32_dpp v60, v60, v60 row_bcast:15 row_mask:0xa bank_mask:0xf
	v_add_f32_dpp v61, v61, v61 row_bcast:15 row_mask:0xa bank_mask:0xf
	s_nop 0
	v_add_f32_dpp v60, v60, v60 row_bcast:31 row_mask:0xc bank_mask:0xf
	v_add_f32_dpp v61, v61, v61 row_bcast:31 row_mask:0xc bank_mask:0xf
	s_nop 0
	v_fma_f32 v60, v60, s22, v64
	v_fma_f32 v61, v61, s22, v64
	v_rsq_f32_e32 v60, v60
	v_rsq_f32_e32 v61, v61
	s_nop 0
	v_readlane_b32 s10, v60, 63
	v_readlane_b32 s11, v61, 63
	s_nop 1
	v_mul_f32_e32 v62, s10, v98
	v_fma_f32 v98, v62, v194, v212
	v_mul_f32_e32 v63, s10, v99
	v_fma_f32 v99, v63, v195, v213
	v_mul_f32_e32 v62, s10, v100
	v_fma_f32 v100, v62, v196, v214
	v_mul_f32_e32 v63, s10, v101
	v_fma_f32 v101, v63, v197, v215
	v_mul_f32_e32 v62, s10, v102
	v_fma_f32 v102, v62, v198, v216
	v_mul_f32_e32 v63, s10, v103
	v_fma_f32 v103, v63, v199, v217
	v_mul_f32_e32 v62, s10, v104
	v_fma_f32 v104, v62, v200, v218
	v_mul_f32_e32 v63, s10, v105
	v_fma_f32 v105, v63, v201, v219
	v_mul_f32_e32 v62, s10, v106
	v_fma_f32 v106, v62, v202, v220
	v_mul_f32_e32 v63, s10, v107
	v_fma_f32 v107, v63, v203, v221
	v_mul_f32_e32 v62, s10, v108
	v_fma_f32 v108, v62, v204, v222
	v_mul_f32_e32 v63, s10, v109
	v_fma_f32 v109, v63, v205, v223
	v_mul_f32_e32 v62, s10, v110
	v_fma_f32 v110, v62, v206, v224
	v_mul_f32_e32 v63, s10, v111
	v_fma_f32 v111, v63, v207, v225
	v_mul_f32_e32 v62, s10, v112
	v_fma_f32 v112, v62, v208, v226
	v_mul_f32_e32 v63, s10, v113
	v_fma_f32 v113, v63, v209, v227
	v_cvt_pk_bf16_f32 v244, v98, v99
	v_cvt_pk_bf16_f32 v245, v100, v101
	v_cvt_pk_bf16_f32 v246, v102, v103
	v_cvt_pk_bf16_f32 v247, v104, v105
	v_cvt_pk_bf16_f32 v248, v106, v107
	v_cvt_pk_bf16_f32 v249, v108, v109
	v_cvt_pk_bf16_f32 v250, v110, v111
	v_cvt_pk_bf16_f32 v251, v112, v113
	global_store_dwordx2 v28, v[244:245], s[2:3]
	global_store_dwordx2 v28, v[246:247], s[2:3] offset:512
	global_store_dwordx2 v28, v[248:249], s[2:3] offset:1024
	global_store_dwordx2 v28, v[250:251], s[2:3] offset:1536
	s_add_u32 s2, s2, 0x60000
	s_addc_u32 s3, s3, 0
	v_mul_f32_e32 v62, s11, v114
	v_fma_f32 v114, v62, v194, v212
	v_mul_f32_e32 v63, s11, v115
	v_fma_f32 v115, v63, v195, v213
	v_mul_f32_e32 v62, s11, v116
	v_fma_f32 v116, v62, v196, v214
	v_mul_f32_e32 v63, s11, v117
	v_fma_f32 v117, v63, v197, v215
	v_mul_f32_e32 v62, s11, v118
	v_fma_f32 v118, v62, v198, v216
	v_mul_f32_e32 v63, s11, v119
	v_fma_f32 v119, v63, v199, v217
	v_mul_f32_e32 v62, s11, v120
	v_fma_f32 v120, v62, v200, v218
	v_mul_f32_e32 v63, s11, v121
	v_fma_f32 v121, v63, v201, v219
	v_mul_f32_e32 v62, s11, v122
	v_fma_f32 v122, v62, v202, v220
	v_mul_f32_e32 v63, s11, v123
	v_fma_f32 v123, v63, v203, v221
	v_mul_f32_e32 v62, s11, v124
	v_fma_f32 v124, v62, v204, v222
	v_mul_f32_e32 v63, s11, v125
	v_fma_f32 v125, v63, v205, v223
	v_mul_f32_e32 v62, s11, v126
	v_fma_f32 v126, v62, v206, v224
	v_mul_f32_e32 v63, s11, v127
	v_fma_f32 v127, v63, v207, v225
	v_mul_f32_e32 v62, s11, v128
	v_fma_f32 v128, v62, v208, v226
	v_mul_f32_e32 v63, s11, v129
	v_fma_f32 v129, v63, v209, v227
	v_cvt_pk_bf16_f32 v10, v114, v115
	v_cvt_pk_bf16_f32 v11, v116, v117
	v_cvt_pk_bf16_f32 v12, v118, v119
	v_cvt_pk_bf16_f32 v13, v120, v121
	v_cvt_pk_bf16_f32 v14, v122, v123
	v_cvt_pk_bf16_f32 v15, v124, v125
	v_cvt_pk_bf16_f32 v16, v126, v127
	v_cvt_pk_bf16_f32 v17, v128, v129
	global_store_dwordx2 v28, v[10:11], s[2:3]
	global_store_dwordx2 v28, v[12:13], s[2:3] offset:512
	global_store_dwordx2 v28, v[14:15], s[2:3] offset:1024
	global_store_dwordx2 v28, v[16:17], s[2:3] offset:1536
	s_add_u32 s2, s2, 0x60000
	s_addc_u32 s3, s3, 0
	global_load_dwordx4 v[98:101], v65, s[0:1]
	global_load_dwordx4 v[102:105], v65, s[0:1] offset:1024
	global_load_dwordx4 v[106:109], v65, s[0:1] offset:2048
	global_load_dwordx4 v[110:113], v65, s[0:1] offset:3072
	s_add_u32 s0, s0, 0xc0000
	s_addc_u32 s1, s1, 0
	global_load_dwordx4 v[114:117], v65, s[0:1]
	global_load_dwordx4 v[118:121], v65, s[0:1] offset:1024
	global_load_dwordx4 v[122:125], v65, s[0:1] offset:2048
	global_load_dwordx4 v[126:129], v65, s[0:1] offset:3072
	s_add_u32 s0, s0, 0xc0000
	s_addc_u32 s1, s1, 0
	s_waitcnt vmcnt(32)
	v_mul_f32_e32 v52, v130, v130
	v_mul_f32_e32 v53, v134, v134
	v_mul_f32_e32 v54, v138, v138
	v_mul_f32_e32 v55, v142, v142
	v_mul_f32_e32 v56, v146, v146
	v_mul_f32_e32 v57, v150, v150
	v_mul_f32_e32 v58, v154, v154
	v_mul_f32_e32 v59, v158, v158
	v_fmac_f32_e32 v52, v131, v131
	v_fmac_f32_e32 v53, v135, v135
	v_fmac_f32_e32 v54, v139, v139
	v_fmac_f32_e32 v55, v143, v143
	v_fmac_f32_e32 v56, v147, v147
	v_fmac_f32_e32 v57, v151, v151
	v_fmac_f32_e32 v58, v155, v155
	v_fmac_f32_e32 v59, v159, v159
	v_fmac_f32_e32 v52, v132, v132
	v_fmac_f32_e32 v53, v136, v136
	v_fmac_f32_e32 v54, v140, v140
	v_fmac_f32_e32 v55, v144, v144
	v_fmac_f32_e32 v56, v148, v148
	v_fmac_f32_e32 v57, v152, v152
	v_fmac_f32_e32 v58, v156, v156
	v_fmac_f32_e32 v59, v160, v160
	v_fmac_f32_e32 v52, v133, v133
	v_fmac_f32_e32 v53, v137, v137
	v_fmac_f32_e32 v54, v141, v141
	v_fmac_f32_e32 v55, v145, v145
	v_fmac_f32_e32 v56, v149, v149
	v_fmac_f32_e32 v57, v153, v153
	v_fmac_f32_e32 v58, v157, v157
	v_fmac_f32_e32 v59, v161, v161
	v_add_f32_e32 v52, v52, v53
	v_add_f32_e32 v54, v54, v55
	v_add_f32_e32 v56, v56, v57
	v_add_f32_e32 v58, v58, v59
	v_add_f32_e32 v60, v52, v54
	v_add_f32_e32 v61, v56, v58
	s_nop 0
	v_add_f32_dpp v60, v60, v60 quad_perm:[1,0,3,2] row_mask:0xf bank_mask:0xf
	v_add_f32_dpp v61, v61, v61 quad_perm:[1,0,3,2] row_mask:0xf bank_mask:0xf
	s_nop 0
	v_add_f32_dpp v60, v60, v60 quad_perm:[2,3,0,1] row_mask:0xf bank_mask:0xf
	v_add_f32_dpp v61, v61, v61 quad_perm:[2,3,0,1] row_mask:0xf bank_mask:0xf
	s_nop 0
	v_add_f32_dpp v60, v60, v60 row_half_mirror row_mask:0xf bank_mask:0xf
	v_add_f32_dpp v61, v61, v61 row_half_mirror row_mask:0xf bank_mask:0xf
	s_nop 0
	v_add_f32_dpp v60, v60, v60 row_mirror row_mask:0xf bank_mask:0xf
	v_add_f32_dpp v61, v61, v61 row_mirror row_mask:0xf bank_mask:0xf
	s_nop 0
	v_add_f32_dpp v60, v60, v60 row_bcast:15 row_mask:0xa bank_mask:0xf
	v_add_f32_dpp v61, v61, v61 row_bcast:15 row_mask:0xa bank_mask:0xf
	s_nop 0
	v_add_f32_dpp v60, v60, v60 row_bcast:31 row_mask:0xc bank_mask:0xf
	v_add_f32_dpp v61, v61, v61 row_bcast:31 row_mask:0xc bank_mask:0xf
	s_nop 0
	v_fma_f32 v60, v60, s22, v64
	v_fma_f32 v61, v61, s22, v64
	v_rsq_f32_e32 v60, v60
	v_rsq_f32_e32 v61, v61
	s_nop 0
	v_readlane_b32 s10, v60, 63
	v_readlane_b32 s11, v61, 63
	s_nop 1
	v_mul_f32_e32 v62, s10, v130
	v_fma_f32 v130, v62, v194, v212
	v_mul_f32_e32 v63, s10, v131
	v_fma_f32 v131, v63, v195, v213
	v_mul_f32_e32 v62, s10, v132
	v_fma_f32 v132, v62, v196, v214
	v_mul_f32_e32 v63, s10, v133
	v_fma_f32 v133, v63, v197, v215
	v_mul_f32_e32 v62, s10, v134
	v_fma_f32 v134, v62, v198, v216
	v_mul_f32_e32 v63, s10, v135
	v_fma_f32 v135, v63, v199, v217
	v_mul_f32_e32 v62, s10, v136
	v_fma_f32 v136, v62, v200, v218
	v_mul_f32_e32 v63, s10, v137
	v_fma_f32 v137, v63, v201, v219
	v_mul_f32_e32 v62, s10, v138
	v_fma_f32 v138, v62, v202, v220
	v_mul_f32_e32 v63, s10, v139
	v_fma_f32 v139, v63, v203, v221
	v_mul_f32_e32 v62, s10, v140
	v_fma_f32 v140, v62, v204, v222
	v_mul_f32_e32 v63, s10, v141
	v_fma_f32 v141, v63, v205, v223
	v_mul_f32_e32 v62, s10, v142
	v_fma_f32 v142, v62, v206, v224
	v_mul_f32_e32 v63, s10, v143
	v_fma_f32 v143, v63, v207, v225
	v_mul_f32_e32 v62, s10, v144
	v_fma_f32 v144, v62, v208, v226
	v_mul_f32_e32 v63, s10, v145
	v_fma_f32 v145, v63, v209, v227
	v_cvt_pk_bf16_f32 v244, v130, v131
	v_cvt_pk_bf16_f32 v245, v132, v133
	v_cvt_pk_bf16_f32 v246, v134, v135
	v_cvt_pk_bf16_f32 v247, v136, v137
	v_cvt_pk_bf16_f32 v248, v138, v139
	v_cvt_pk_bf16_f32 v249, v140, v141
	v_cvt_pk_bf16_f32 v250, v142, v143
	v_cvt_pk_bf16_f32 v251, v144, v145
	global_store_dwordx2 v28, v[244:245], s[2:3]
	global_store_dwordx2 v28, v[246:247], s[2:3] offset:512
	global_store_dwordx2 v28, v[248:249], s[2:3] offset:1024
	global_store_dwordx2 v28, v[250:251], s[2:3] offset:1536
	s_add_u32 s2, s2, 0x60000
	s_addc_u32 s3, s3, 0
	v_mul_f32_e32 v62, s11, v146
	v_fma_f32 v146, v62, v194, v212
	v_mul_f32_e32 v63, s11, v147
	v_fma_f32 v147, v63, v195, v213
	v_mul_f32_e32 v62, s11, v148
	v_fma_f32 v148, v62, v196, v214
	v_mul_f32_e32 v63, s11, v149
	v_fma_f32 v149, v63, v197, v215
	v_mul_f32_e32 v62, s11, v150
	v_fma_f32 v150, v62, v198, v216
	v_mul_f32_e32 v63, s11, v151
	v_fma_f32 v151, v63, v199, v217
	v_mul_f32_e32 v62, s11, v152
	v_fma_f32 v152, v62, v200, v218
	v_mul_f32_e32 v63, s11, v153
	v_fma_f32 v153, v63, v201, v219
	v_mul_f32_e32 v62, s11, v154
	v_fma_f32 v154, v62, v202, v220
	v_mul_f32_e32 v63, s11, v155
	v_fma_f32 v155, v63, v203, v221
	v_mul_f32_e32 v62, s11, v156
	v_fma_f32 v156, v62, v204, v222
	v_mul_f32_e32 v63, s11, v157
	v_fma_f32 v157, v63, v205, v223
	v_mul_f32_e32 v62, s11, v158
	v_fma_f32 v158, v62, v206, v224
	v_mul_f32_e32 v63, s11, v159
	v_fma_f32 v159, v63, v207, v225
	v_mul_f32_e32 v62, s11, v160
	v_fma_f32 v160, v62, v208, v226
	v_mul_f32_e32 v63, s11, v161
	v_fma_f32 v161, v63, v209, v227
	v_cvt_pk_bf16_f32 v10, v146, v147
	v_cvt_pk_bf16_f32 v11, v148, v149
	v_cvt_pk_bf16_f32 v12, v150, v151
	v_cvt_pk_bf16_f32 v13, v152, v153
	v_cvt_pk_bf16_f32 v14, v154, v155
	v_cvt_pk_bf16_f32 v15, v156, v157
	v_cvt_pk_bf16_f32 v16, v158, v159
	v_cvt_pk_bf16_f32 v17, v160, v161
	global_store_dwordx2 v28, v[10:11], s[2:3]
	global_store_dwordx2 v28, v[12:13], s[2:3] offset:512
	global_store_dwordx2 v28, v[14:15], s[2:3] offset:1024
	global_store_dwordx2 v28, v[16:17], s[2:3] offset:1536
	s_add_u32 s2, s2, 0x60000
	s_addc_u32 s3, s3, 0
	global_load_dwordx4 v[130:133], v65, s[0:1]
	global_load_dwordx4 v[134:137], v65, s[0:1] offset:1024
	global_load_dwordx4 v[138:141], v65, s[0:1] offset:2048
	global_load_dwordx4 v[142:145], v65, s[0:1] offset:3072
	s_add_u32 s0, s0, 0xc0000
	s_addc_u32 s1, s1, 0
	global_load_dwordx4 v[146:149], v65, s[0:1]
	global_load_dwordx4 v[150:153], v65, s[0:1] offset:1024
	global_load_dwordx4 v[154:157], v65, s[0:1] offset:2048
	global_load_dwordx4 v[158:161], v65, s[0:1] offset:3072
	s_add_u32 s0, s0, 0xc0000
	s_addc_u32 s1, s1, 0
	s_waitcnt vmcnt(32)
	v_mul_f32_e32 v52, v162, v162
	v_mul_f32_e32 v53, v166, v166
	v_mul_f32_e32 v54, v170, v170
	v_mul_f32_e32 v55, v174, v174
	v_mul_f32_e32 v56, v178, v178
	v_mul_f32_e32 v57, v182, v182
	v_mul_f32_e32 v58, v186, v186
	v_mul_f32_e32 v59, v190, v190
	v_fmac_f32_e32 v52, v163, v163
	v_fmac_f32_e32 v53, v167, v167
	v_fmac_f32_e32 v54, v171, v171
	v_fmac_f32_e32 v55, v175, v175
	v_fmac_f32_e32 v56, v179, v179
	v_fmac_f32_e32 v57, v183, v183
	v_fmac_f32_e32 v58, v187, v187
	v_fmac_f32_e32 v59, v191, v191
	v_fmac_f32_e32 v52, v164, v164
	v_fmac_f32_e32 v53, v168, v168
	v_fmac_f32_e32 v54, v172, v172
	v_fmac_f32_e32 v55, v176, v176
	v_fmac_f32_e32 v56, v180, v180
	v_fmac_f32_e32 v57, v184, v184
	v_fmac_f32_e32 v58, v188, v188
	v_fmac_f32_e32 v59, v192, v192
	v_fmac_f32_e32 v52, v165, v165
	v_fmac_f32_e32 v53, v169, v169
	v_fmac_f32_e32 v54, v173, v173
	v_fmac_f32_e32 v55, v177, v177
	v_fmac_f32_e32 v56, v181, v181
	v_fmac_f32_e32 v57, v185, v185
	v_fmac_f32_e32 v58, v189, v189
	v_fmac_f32_e32 v59, v193, v193
	v_add_f32_e32 v52, v52, v53
	v_add_f32_e32 v54, v54, v55
	v_add_f32_e32 v56, v56, v57
	v_add_f32_e32 v58, v58, v59
	v_add_f32_e32 v60, v52, v54
	v_add_f32_e32 v61, v56, v58
	s_nop 0
	v_add_f32_dpp v60, v60, v60 quad_perm:[1,0,3,2] row_mask:0xf bank_mask:0xf
	v_add_f32_dpp v61, v61, v61 quad_perm:[1,0,3,2] row_mask:0xf bank_mask:0xf
	s_nop 0
	v_add_f32_dpp v60, v60, v60 quad_perm:[2,3,0,1] row_mask:0xf bank_mask:0xf
	v_add_f32_dpp v61, v61, v61 quad_perm:[2,3,0,1] row_mask:0xf bank_mask:0xf
	s_nop 0
	v_add_f32_dpp v60, v60, v60 row_half_mirror row_mask:0xf bank_mask:0xf
	v_add_f32_dpp v61, v61, v61 row_half_mirror row_mask:0xf bank_mask:0xf
	s_nop 0
	v_add_f32_dpp v60, v60, v60 row_mirror row_mask:0xf bank_mask:0xf
	v_add_f32_dpp v61, v61, v61 row_mirror row_mask:0xf bank_mask:0xf
	s_nop 0
	v_add_f32_dpp v60, v60, v60 row_bcast:15 row_mask:0xa bank_mask:0xf
	v_add_f32_dpp v61, v61, v61 row_bcast:15 row_mask:0xa bank_mask:0xf
	s_nop 0
	v_add_f32_dpp v60, v60, v60 row_bcast:31 row_mask:0xc bank_mask:0xf
	v_add_f32_dpp v61, v61, v61 row_bcast:31 row_mask:0xc bank_mask:0xf
	s_nop 0
	v_fma_f32 v60, v60, s22, v64
	v_fma_f32 v61, v61, s22, v64
	v_rsq_f32_e32 v60, v60
	v_rsq_f32_e32 v61, v61
	s_nop 0
	v_readlane_b32 s10, v60, 63
	v_readlane_b32 s11, v61, 63
	s_nop 1
	s_cmp_lt_u32 s5, 0x80
	s_cbranch_scc1 .Ln2_r10_b0
	v_mul_f32_e32 v62, s10, v162
	v_fma_f32 v162, v62, v228, v36
	v_mul_f32_e32 v63, s10, v163
	v_fma_f32 v163, v63, v229, v37
	v_mul_f32_e32 v62, s10, v164
	v_fma_f32 v164, v62, v230, v38
	v_mul_f32_e32 v63, s10, v165
	v_fma_f32 v165, v63, v231, v39
	v_mul_f32_e32 v62, s10, v166
	v_fma_f32 v166, v62, v232, v40
	v_mul_f32_e32 v63, s10, v167
	v_fma_f32 v167, v63, v233, v41
	v_mul_f32_e32 v62, s10, v168
	v_fma_f32 v168, v62, v234, v42
	v_mul_f32_e32 v63, s10, v169
	v_fma_f32 v169, v63, v235, v43
	v_mul_f32_e32 v62, s10, v170
	v_fma_f32 v170, v62, v236, v44
	v_mul_f32_e32 v63, s10, v171
	v_fma_f32 v171, v63, v237, v45
	v_mul_f32_e32 v62, s10, v172
	v_fma_f32 v172, v62, v238, v46
	v_mul_f32_e32 v63, s10, v173
	v_fma_f32 v173, v63, v239, v47
	v_mul_f32_e32 v62, s10, v174
	v_fma_f32 v174, v62, v240, v48
	v_mul_f32_e32 v63, s10, v175
	v_fma_f32 v175, v63, v241, v49
	v_mul_f32_e32 v62, s10, v176
	v_fma_f32 v176, v62, v242, v50
	v_mul_f32_e32 v63, s10, v177
	v_fma_f32 v177, v63, v243, v51
	s_branch .Ln2_r10_done
.Ln2_r10_b0:
	v_mul_f32_e32 v62, s10, v162
	v_fma_f32 v162, v62, v194, v212
	v_mul_f32_e32 v63, s10, v163
	v_fma_f32 v163, v63, v195, v213
	v_mul_f32_e32 v62, s10, v164
	v_fma_f32 v164, v62, v196, v214
	v_mul_f32_e32 v63, s10, v165
	v_fma_f32 v165, v63, v197, v215
	v_mul_f32_e32 v62, s10, v166
	v_fma_f32 v166, v62, v198, v216
	v_mul_f32_e32 v63, s10, v167
	v_fma_f32 v167, v63, v199, v217
	v_mul_f32_e32 v62, s10, v168
	v_fma_f32 v168, v62, v200, v218
	v_mul_f32_e32 v63, s10, v169
	v_fma_f32 v169, v63, v201, v219
	v_mul_f32_e32 v62, s10, v170
	v_fma_f32 v170, v62, v202, v220
	v_mul_f32_e32 v63, s10, v171
	v_fma_f32 v171, v63, v203, v221
	v_mul_f32_e32 v62, s10, v172
	v_fma_f32 v172, v62, v204, v222
	v_mul_f32_e32 v63, s10, v173
	v_fma_f32 v173, v63, v205, v223
	v_mul_f32_e32 v62, s10, v174
	v_fma_f32 v174, v62, v206, v224
	v_mul_f32_e32 v63, s10, v175
	v_fma_f32 v175, v63, v207, v225
	v_mul_f32_e32 v62, s10, v176
	v_fma_f32 v176, v62, v208, v226
	v_mul_f32_e32 v63, s10, v177
	v_fma_f32 v177, v63, v209, v227
.Ln2_r10_done:
	v_cvt_pk_bf16_f32 v244, v162, v163
	v_cvt_pk_bf16_f32 v245, v164, v165
	v_cvt_pk_bf16_f32 v246, v166, v167
	v_cvt_pk_bf16_f32 v247, v168, v169
	v_cvt_pk_bf16_f32 v248, v170, v171
	v_cvt_pk_bf16_f32 v249, v172, v173
	v_cvt_pk_bf16_f32 v250, v174, v175
	v_cvt_pk_bf16_f32 v251, v176, v177
	global_store_dwordx2 v28, v[244:245], s[2:3]
	global_store_dwordx2 v28, v[246:247], s[2:3] offset:512
	global_store_dwordx2 v28, v[248:249], s[2:3] offset:1024
	global_store_dwordx2 v28, v[250:251], s[2:3] offset:1536
	s_add_u32 s2, s2, 0x60000
	s_addc_u32 s3, s3, 0
	v_mul_f32_e32 v62, s11, v178
	v_fma_f32 v178, v62, v228, v36
	v_mul_f32_e32 v63, s11, v179
	v_fma_f32 v179, v63, v229, v37
	v_mul_f32_e32 v62, s11, v180
	v_fma_f32 v180, v62, v230, v38
	v_mul_f32_e32 v63, s11, v181
	v_fma_f32 v181, v63, v231, v39
	v_mul_f32_e32 v62, s11, v182
	v_fma_f32 v182, v62, v232, v40
	v_mul_f32_e32 v63, s11, v183
	v_fma_f32 v183, v63, v233, v41
	v_mul_f32_e32 v62, s11, v184
	v_fma_f32 v184, v62, v234, v42
	v_mul_f32_e32 v63, s11, v185
	v_fma_f32 v185, v63, v235, v43
	v_mul_f32_e32 v62, s11, v186
	v_fma_f32 v186, v62, v236, v44
	v_mul_f32_e32 v63, s11, v187
	v_fma_f32 v187, v63, v237, v45
	v_mul_f32_e32 v62, s11, v188
	v_fma_f32 v188, v62, v238, v46
	v_mul_f32_e32 v63, s11, v189
	v_fma_f32 v189, v63, v239, v47
	v_mul_f32_e32 v62, s11, v190
	v_fma_f32 v190, v62, v240, v48
	v_mul_f32_e32 v63, s11, v191
	v_fma_f32 v191, v63, v241, v49
	v_mul_f32_e32 v62, s11, v192
	v_fma_f32 v192, v62, v242, v50
	v_mul_f32_e32 v63, s11, v193
	v_fma_f32 v193, v63, v243, v51
	v_cvt_pk_bf16_f32 v10, v178, v179
	v_cvt_pk_bf16_f32 v11, v180, v181
	v_cvt_pk_bf16_f32 v12, v182, v183
	v_cvt_pk_bf16_f32 v13, v184, v185
	v_cvt_pk_bf16_f32 v14, v186, v187
	v_cvt_pk_bf16_f32 v15, v188, v189
	v_cvt_pk_bf16_f32 v16, v190, v191
	v_cvt_pk_bf16_f32 v17, v192, v193
	global_store_dwordx2 v28, v[10:11], s[2:3]
	global_store_dwordx2 v28, v[12:13], s[2:3] offset:512
	global_store_dwordx2 v28, v[14:15], s[2:3] offset:1024
	global_store_dwordx2 v28, v[16:17], s[2:3] offset:1536
	s_add_u32 s2, s2, 0x60000
	s_addc_u32 s3, s3, 0
	global_load_dwordx4 v[162:165], v65, s[0:1]
	global_load_dwordx4 v[166:169], v65, s[0:1] offset:1024
	global_load_dwordx4 v[170:173], v65, s[0:1] offset:2048
	global_load_dwordx4 v[174:177], v65, s[0:1] offset:3072
	s_add_u32 s0, s0, 0xc0000
	s_addc_u32 s1, s1, 0
	global_load_dwordx4 v[178:181], v65, s[0:1]
	global_load_dwordx4 v[182:185], v65, s[0:1] offset:1024
	global_load_dwordx4 v[186:189], v65, s[0:1] offset:2048
	global_load_dwordx4 v[190:193], v65, s[0:1] offset:3072
	s_add_u32 s0, s0, 0xc0000
	s_addc_u32 s1, s1, 0
	s_waitcnt vmcnt(32)
	v_mul_f32_e32 v52, v98, v98
	v_mul_f32_e32 v53, v102, v102
	v_mul_f32_e32 v54, v106, v106
	v_mul_f32_e32 v55, v110, v110
	v_mul_f32_e32 v56, v114, v114
	v_mul_f32_e32 v57, v118, v118
	v_mul_f32_e32 v58, v122, v122
	v_mul_f32_e32 v59, v126, v126
	v_fmac_f32_e32 v52, v99, v99
	v_fmac_f32_e32 v53, v103, v103
	v_fmac_f32_e32 v54, v107, v107
	v_fmac_f32_e32 v55, v111, v111
	v_fmac_f32_e32 v56, v115, v115
	v_fmac_f32_e32 v57, v119, v119
	v_fmac_f32_e32 v58, v123, v123
	v_fmac_f32_e32 v59, v127, v127
	v_fmac_f32_e32 v52, v100, v100
	v_fmac_f32_e32 v53, v104, v104
	v_fmac_f32_e32 v54, v108, v108
	v_fmac_f32_e32 v55, v112, v112
	v_fmac_f32_e32 v56, v116, v116
	v_fmac_f32_e32 v57, v120, v120
	v_fmac_f32_e32 v58, v124, v124
	v_fmac_f32_e32 v59, v128, v128
	v_fmac_f32_e32 v52, v101, v101
	v_fmac_f32_e32 v53, v105, v105
	v_fmac_f32_e32 v54, v109, v109
	v_fmac_f32_e32 v55, v113, v113
	v_fmac_f32_e32 v56, v117, v117
	v_fmac_f32_e32 v57, v121, v121
	v_fmac_f32_e32 v58, v125, v125
	v_fmac_f32_e32 v59, v129, v129
	v_add_f32_e32 v52, v52, v53
	v_add_f32_e32 v54, v54, v55
	v_add_f32_e32 v56, v56, v57
	v_add_f32_e32 v58, v58, v59
	v_add_f32_e32 v60, v52, v54
	v_add_f32_e32 v61, v56, v58
	s_nop 0
	v_add_f32_dpp v60, v60, v60 quad_perm:[1,0,3,2] row_mask:0xf bank_mask:0xf
	v_add_f32_dpp v61, v61, v61 quad_perm:[1,0,3,2] row_mask:0xf bank_mask:0xf
	s_nop 0
	v_add_f32_dpp v60, v60, v60 quad_perm:[2,3,0,1] row_mask:0xf bank_mask:0xf
	v_add_f32_dpp v61, v61, v61 quad_perm:[2,3,0,1] row_mask:0xf bank_mask:0xf
	s_nop 0
	v_add_f32_dpp v60, v60, v60 row_half_mirror row_mask:0xf bank_mask:0xf
	v_add_f32_dpp v61, v61, v61 row_half_mirror row_mask:0xf bank_mask:0xf
	s_nop 0
	v_add_f32_dpp v60, v60, v60 row_mirror row_mask:0xf bank_mask:0xf
	v_add_f32_dpp v61, v61, v61 row_mirror row_mask:0xf bank_mask:0xf
	s_nop 0
	v_add_f32_dpp v60, v60, v60 row_bcast:15 row_mask:0xa bank_mask:0xf
	v_add_f32_dpp v61, v61, v61 row_bcast:15 row_mask:0xa bank_mask:0xf
	s_nop 0
	v_add_f32_dpp v60, v60, v60 row_bcast:31 row_mask:0xc bank_mask:0xf
	v_add_f32_dpp v61, v61, v61 row_bcast:31 row_mask:0xc bank_mask:0xf
	s_nop 0
	v_fma_f32 v60, v60, s22, v64
	v_fma_f32 v61, v61, s22, v64
	v_rsq_f32_e32 v60, v60
	v_rsq_f32_e32 v61, v61
	s_nop 0
	v_readlane_b32 s10, v60, 63
	v_readlane_b32 s11, v61, 63
	s_nop 1
	v_mul_f32_e32 v62, s10, v98
	v_fma_f32 v98, v62, v228, v36
	v_mul_f32_e32 v63, s10, v99
	v_fma_f32 v99, v63, v229, v37
	v_mul_f32_e32 v62, s10, v100
	v_fma_f32 v100, v62, v230, v38
	v_mul_f32_e32 v63, s10, v101
	v_fma_f32 v101, v63, v231, v39
	v_mul_f32_e32 v62, s10, v102
	v_fma_f32 v102, v62, v232, v40
	v_mul_f32_e32 v63, s10, v103
	v_fma_f32 v103, v63, v233, v41
	v_mul_f32_e32 v62, s10, v104
	v_fma_f32 v104, v62, v234, v42
	v_mul_f32_e32 v63, s10, v105
	v_fma_f32 v105, v63, v235, v43
	v_mul_f32_e32 v62, s10, v106
	v_fma_f32 v106, v62, v236, v44
	v_mul_f32_e32 v63, s10, v107
	v_fma_f32 v107, v63, v237, v45
	v_mul_f32_e32 v62, s10, v108
	v_fma_f32 v108, v62, v238, v46
	v_mul_f32_e32 v63, s10, v109
	v_fma_f32 v109, v63, v239, v47
	v_mul_f32_e32 v62, s10, v110
	v_fma_f32 v110, v62, v240, v48
	v_mul_f32_e32 v63, s10, v111
	v_fma_f32 v111, v63, v241, v49
	v_mul_f32_e32 v62, s10, v112
	v_fma_f32 v112, v62, v242, v50
	v_mul_f32_e32 v63, s10, v113
	v_fma_f32 v113, v63, v243, v51
	v_cvt_pk_bf16_f32 v244, v98, v99
	v_cvt_pk_bf16_f32 v245, v100, v101
	v_cvt_pk_bf16_f32 v246, v102, v103
	v_cvt_pk_bf16_f32 v247, v104, v105
	v_cvt_pk_bf16_f32 v248, v106, v107
	v_cvt_pk_bf16_f32 v249, v108, v109
	v_cvt_pk_bf16_f32 v250, v110, v111
	v_cvt_pk_bf16_f32 v251, v112, v113
	global_store_dwordx2 v28, v[244:245], s[2:3]
	global_store_dwordx2 v28, v[246:247], s[2:3] offset:512
	global_store_dwordx2 v28, v[248:249], s[2:3] offset:1024
	global_store_dwordx2 v28, v[250:251], s[2:3] offset:1536
	s_add_u32 s2, s2, 0x60000
	s_addc_u32 s3, s3, 0
	v_mul_f32_e32 v62, s11, v114
	v_fma_f32 v114, v62, v228, v36
	v_mul_f32_e32 v63, s11, v115
	v_fma_f32 v115, v63, v229, v37
	v_mul_f32_e32 v62, s11, v116
	v_fma_f32 v116, v62, v230, v38
	v_mul_f32_e32 v63, s11, v117
	v_fma_f32 v117, v63, v231, v39
	v_mul_f32_e32 v62, s11, v118
	v_fma_f32 v118, v62, v232, v40
	v_mul_f32_e32 v63, s11, v119
	v_fma_f32 v119, v63, v233, v41
	v_mul_f32_e32 v62, s11, v120
	v_fma_f32 v120, v62, v234, v42
	v_mul_f32_e32 v63, s11, v121
	v_fma_f32 v121, v63, v235, v43
	v_mul_f32_e32 v62, s11, v122
	v_fma_f32 v122, v62, v236, v44
	v_mul_f32_e32 v63, s11, v123
	v_fma_f32 v123, v63, v237, v45
	v_mul_f32_e32 v62, s11, v124
	v_fma_f32 v124, v62, v238, v46
	v_mul_f32_e32 v63, s11, v125
	v_fma_f32 v125, v63, v239, v47
	v_mul_f32_e32 v62, s11, v126
	v_fma_f32 v126, v62, v240, v48
	v_mul_f32_e32 v63, s11, v127
	v_fma_f32 v127, v63, v241, v49
	v_mul_f32_e32 v62, s11, v128
	v_fma_f32 v128, v62, v242, v50
	v_mul_f32_e32 v63, s11, v129
	v_fma_f32 v129, v63, v243, v51
	v_cvt_pk_bf16_f32 v10, v114, v115
	v_cvt_pk_bf16_f32 v11, v116, v117
	v_cvt_pk_bf16_f32 v12, v118, v119
	v_cvt_pk_bf16_f32 v13, v120, v121
	v_cvt_pk_bf16_f32 v14, v122, v123
	v_cvt_pk_bf16_f32 v15, v124, v125
	v_cvt_pk_bf16_f32 v16, v126, v127
	v_cvt_pk_bf16_f32 v17, v128, v129
	global_store_dwordx2 v28, v[10:11], s[2:3]
	global_store_dwordx2 v28, v[12:13], s[2:3] offset:512
	global_store_dwordx2 v28, v[14:15], s[2:3] offset:1024
	global_store_dwordx2 v28, v[16:17], s[2:3] offset:1536
	s_add_u32 s2, s2, 0x60000
	s_addc_u32 s3, s3, 0
	global_load_dwordx4 v[98:101], v65, s[0:1]
	global_load_dwordx4 v[102:105], v65, s[0:1] offset:1024
	global_load_dwordx4 v[106:109], v65, s[0:1] offset:2048
	global_load_dwordx4 v[110:113], v65, s[0:1] offset:3072
	s_add_u32 s0, s0, 0xc0000
	s_addc_u32 s1, s1, 0
	global_load_dwordx4 v[114:117], v65, s[0:1]
	global_load_dwordx4 v[118:121], v65, s[0:1] offset:1024
	global_load_dwordx4 v[122:125], v65, s[0:1] offset:2048
	global_load_dwordx4 v[126:129], v65, s[0:1] offset:3072
	s_add_u32 s0, s0, 0xc0000
	s_addc_u32 s1, s1, 0
	s_waitcnt vmcnt(32)
	v_mul_f32_e32 v52, v130, v130
	v_mul_f32_e32 v53, v134, v134
	v_mul_f32_e32 v54, v138, v138
	v_mul_f32_e32 v55, v142, v142
	v_mul_f32_e32 v56, v146, v146
	v_mul_f32_e32 v57, v150, v150
	v_mul_f32_e32 v58, v154, v154
	v_mul_f32_e32 v59, v158, v158
	v_fmac_f32_e32 v52, v131, v131
	v_fmac_f32_e32 v53, v135, v135
	v_fmac_f32_e32 v54, v139, v139
	v_fmac_f32_e32 v55, v143, v143
	v_fmac_f32_e32 v56, v147, v147
	v_fmac_f32_e32 v57, v151, v151
	v_fmac_f32_e32 v58, v155, v155
	v_fmac_f32_e32 v59, v159, v159
	v_fmac_f32_e32 v52, v132, v132
	v_fmac_f32_e32 v53, v136, v136
	v_fmac_f32_e32 v54, v140, v140
	v_fmac_f32_e32 v55, v144, v144
	v_fmac_f32_e32 v56, v148, v148
	v_fmac_f32_e32 v57, v152, v152
	v_fmac_f32_e32 v58, v156, v156
	v_fmac_f32_e32 v59, v160, v160
	v_fmac_f32_e32 v52, v133, v133
	v_fmac_f32_e32 v53, v137, v137
	v_fmac_f32_e32 v54, v141, v141
	v_fmac_f32_e32 v55, v145, v145
	v_fmac_f32_e32 v56, v149, v149
	v_fmac_f32_e32 v57, v153, v153
	v_fmac_f32_e32 v58, v157, v157
	v_fmac_f32_e32 v59, v161, v161
	v_add_f32_e32 v52, v52, v53
	v_add_f32_e32 v54, v54, v55
	v_add_f32_e32 v56, v56, v57
	v_add_f32_e32 v58, v58, v59
	v_add_f32_e32 v60, v52, v54
	v_add_f32_e32 v61, v56, v58
	s_nop 0
	v_add_f32_dpp v60, v60, v60 quad_perm:[1,0,3,2] row_mask:0xf bank_mask:0xf
	v_add_f32_dpp v61, v61, v61 quad_perm:[1,0,3,2] row_mask:0xf bank_mask:0xf
	s_nop 0
	v_add_f32_dpp v60, v60, v60 quad_perm:[2,3,0,1] row_mask:0xf bank_mask:0xf
	v_add_f32_dpp v61, v61, v61 quad_perm:[2,3,0,1] row_mask:0xf bank_mask:0xf
	s_nop 0
	v_add_f32_dpp v60, v60, v60 row_half_mirror row_mask:0xf bank_mask:0xf
	v_add_f32_dpp v61, v61, v61 row_half_mirror row_mask:0xf bank_mask:0xf
	s_nop 0
	v_add_f32_dpp v60, v60, v60 row_mirror row_mask:0xf bank_mask:0xf
	v_add_f32_dpp v61, v61, v61 row_mirror row_mask:0xf bank_mask:0xf
	s_nop 0
	v_add_f32_dpp v60, v60, v60 row_bcast:15 row_mask:0xa bank_mask:0xf
	v_add_f32_dpp v61, v61, v61 row_bcast:15 row_mask:0xa bank_mask:0xf
	s_nop 0
	v_add_f32_dpp v60, v60, v60 row_bcast:31 row_mask:0xc bank_mask:0xf
	v_add_f32_dpp v61, v61, v61 row_bcast:31 row_mask:0xc bank_mask:0xf
	s_nop 0
	v_fma_f32 v60, v60, s22, v64
	v_fma_f32 v61, v61, s22, v64
	v_rsq_f32_e32 v60, v60
	v_rsq_f32_e32 v61, v61
	s_nop 0
	v_readlane_b32 s10, v60, 63
	v_readlane_b32 s11, v61, 63
	s_nop 1
	v_mul_f32_e32 v62, s10, v130
	v_fma_f32 v130, v62, v228, v36
	v_mul_f32_e32 v63, s10, v131
	v_fma_f32 v131, v63, v229, v37
	v_mul_f32_e32 v62, s10, v132
	v_fma_f32 v132, v62, v230, v38
	v_mul_f32_e32 v63, s10, v133
	v_fma_f32 v133, v63, v231, v39
	v_mul_f32_e32 v62, s10, v134
	v_fma_f32 v134, v62, v232, v40
	v_mul_f32_e32 v63, s10, v135
	v_fma_f32 v135, v63, v233, v41
	v_mul_f32_e32 v62, s10, v136
	v_fma_f32 v136, v62, v234, v42
	v_mul_f32_e32 v63, s10, v137
	v_fma_f32 v137, v63, v235, v43
	v_mul_f32_e32 v62, s10, v138
	v_fma_f32 v138, v62, v236, v44
	v_mul_f32_e32 v63, s10, v139
	v_fma_f32 v139, v63, v237, v45
	v_mul_f32_e32 v62, s10, v140
	v_fma_f32 v140, v62, v238, v46
	v_mul_f32_e32 v63, s10, v141
	v_fma_f32 v141, v63, v239, v47
	v_mul_f32_e32 v62, s10, v142
	v_fma_f32 v142, v62, v240, v48
	v_mul_f32_e32 v63, s10, v143
	v_fma_f32 v143, v63, v241, v49
	v_mul_f32_e32 v62, s10, v144
	v_fma_f32 v144, v62, v242, v50
	v_mul_f32_e32 v63, s10, v145
	v_fma_f32 v145, v63, v243, v51
	v_cvt_pk_bf16_f32 v244, v130, v131
	v_cvt_pk_bf16_f32 v245, v132, v133
	v_cvt_pk_bf16_f32 v246, v134, v135
	v_cvt_pk_bf16_f32 v247, v136, v137
	v_cvt_pk_bf16_f32 v248, v138, v139
	v_cvt_pk_bf16_f32 v249, v140, v141
	v_cvt_pk_bf16_f32 v250, v142, v143
	v_cvt_pk_bf16_f32 v251, v144, v145
	global_store_dwordx2 v28, v[244:245], s[2:3]
	global_store_dwordx2 v28, v[246:247], s[2:3] offset:512
	global_store_dwordx2 v28, v[248:249], s[2:3] offset:1024
	global_store_dwordx2 v28, v[250:251], s[2:3] offset:1536
	s_add_u32 s2, s2, 0x60000
	s_addc_u32 s3, s3, 0
	v_mul_f32_e32 v62, s11, v146
	v_fma_f32 v146, v62, v228, v36
	v_mul_f32_e32 v63, s11, v147
	v_fma_f32 v147, v63, v229, v37
	v_mul_f32_e32 v62, s11, v148
	v_fma_f32 v148, v62, v230, v38
	v_mul_f32_e32 v63, s11, v149
	v_fma_f32 v149, v63, v231, v39
	v_mul_f32_e32 v62, s11, v150
	v_fma_f32 v150, v62, v232, v40
	v_mul_f32_e32 v63, s11, v151
	v_fma_f32 v151, v63, v233, v41
	v_mul_f32_e32 v62, s11, v152
	v_fma_f32 v152, v62, v234, v42
	v_mul_f32_e32 v63, s11, v153
	v_fma_f32 v153, v63, v235, v43
	v_mul_f32_e32 v62, s11, v154
	v_fma_f32 v154, v62, v236, v44
	v_mul_f32_e32 v63, s11, v155
	v_fma_f32 v155, v63, v237, v45
	v_mul_f32_e32 v62, s11, v156
	v_fma_f32 v156, v62, v238, v46
	v_mul_f32_e32 v63, s11, v157
	v_fma_f32 v157, v63, v239, v47
	v_mul_f32_e32 v62, s11, v158
	v_fma_f32 v158, v62, v240, v48
	v_mul_f32_e32 v63, s11, v159
	v_fma_f32 v159, v63, v241, v49
	v_mul_f32_e32 v62, s11, v160
	v_fma_f32 v160, v62, v242, v50
	v_mul_f32_e32 v63, s11, v161
	v_fma_f32 v161, v63, v243, v51
	v_cvt_pk_bf16_f32 v10, v146, v147
	v_cvt_pk_bf16_f32 v11, v148, v149
	v_cvt_pk_bf16_f32 v12, v150, v151
	v_cvt_pk_bf16_f32 v13, v152, v153
	v_cvt_pk_bf16_f32 v14, v154, v155
	v_cvt_pk_bf16_f32 v15, v156, v157
	v_cvt_pk_bf16_f32 v16, v158, v159
	v_cvt_pk_bf16_f32 v17, v160, v161
	global_store_dwordx2 v28, v[10:11], s[2:3]
	global_store_dwordx2 v28, v[12:13], s[2:3] offset:512
	global_store_dwordx2 v28, v[14:15], s[2:3] offset:1024
	global_store_dwordx2 v28, v[16:17], s[2:3] offset:1536
	s_add_u32 s2, s2, 0x60000
	s_addc_u32 s3, s3, 0
	global_load_dwordx4 v[130:133], v65, s[0:1]
	global_load_dwordx4 v[134:137], v65, s[0:1] offset:1024
	global_load_dwordx4 v[138:141], v65, s[0:1] offset:2048
	global_load_dwordx4 v[142:145], v65, s[0:1] offset:3072
	s_add_u32 s0, s0, s23
	s_addc_u32 s1, s1, 0
	global_load_dwordx4 v[146:149], v65, s[0:1]
	global_load_dwordx4 v[150:153], v65, s[0:1] offset:1024
	global_load_dwordx4 v[154:157], v65, s[0:1] offset:2048
	global_load_dwordx4 v[158:161], v65, s[0:1] offset:3072
	s_waitcnt vmcnt(32)
	v_mul_f32_e32 v52, v162, v162
	v_mul_f32_e32 v53, v166, v166
	v_mul_f32_e32 v54, v170, v170
	v_mul_f32_e32 v55, v174, v174
	v_mul_f32_e32 v56, v178, v178
	v_mul_f32_e32 v57, v182, v182
	v_mul_f32_e32 v58, v186, v186
	v_mul_f32_e32 v59, v190, v190
	v_fmac_f32_e32 v52, v163, v163
	v_fmac_f32_e32 v53, v167, v167
	v_fmac_f32_e32 v54, v171, v171
	v_fmac_f32_e32 v55, v175, v175
	v_fmac_f32_e32 v56, v179, v179
	v_fmac_f32_e32 v57, v183, v183
	v_fmac_f32_e32 v58, v187, v187
	v_fmac_f32_e32 v59, v191, v191
	v_fmac_f32_e32 v52, v164, v164
	v_fmac_f32_e32 v53, v168, v168
	v_fmac_f32_e32 v54, v172, v172
	v_fmac_f32_e32 v55, v176, v176
	v_fmac_f32_e32 v56, v180, v180
	v_fmac_f32_e32 v57, v184, v184
	v_fmac_f32_e32 v58, v188, v188
	v_fmac_f32_e32 v59, v192, v192
	v_fmac_f32_e32 v52, v165, v165
	v_fmac_f32_e32 v53, v169, v169
	v_fmac_f32_e32 v54, v173, v173
	v_fmac_f32_e32 v55, v177, v177
	v_fmac_f32_e32 v56, v181, v181
	v_fmac_f32_e32 v57, v185, v185
	v_fmac_f32_e32 v58, v189, v189
	v_fmac_f32_e32 v59, v193, v193
	v_add_f32_e32 v52, v52, v53
	v_add_f32_e32 v54, v54, v55
	v_add_f32_e32 v56, v56, v57
	v_add_f32_e32 v58, v58, v59
	v_add_f32_e32 v60, v52, v54
	v_add_f32_e32 v61, v56, v58
	s_nop 0
	v_add_f32_dpp v60, v60, v60 quad_perm:[1,0,3,2] row_mask:0xf bank_mask:0xf
	v_add_f32_dpp v61, v61, v61 quad_perm:[1,0,3,2] row_mask:0xf bank_mask:0xf
	s_nop 0
	v_add_f32_dpp v60, v60, v60 quad_perm:[2,3,0,1] row_mask:0xf bank_mask:0xf
	v_add_f32_dpp v61, v61, v61 quad_perm:[2,3,0,1] row_mask:0xf bank_mask:0xf
	s_nop 0
	v_add_f32_dpp v60, v60, v60 row_half_mirror row_mask:0xf bank_mask:0xf
	v_add_f32_dpp v61, v61, v61 row_half_mirror row_mask:0xf bank_mask:0xf
	s_nop 0
	v_add_f32_dpp v60, v60, v60 row_mirror row_mask:0xf bank_mask:0xf
	v_add_f32_dpp v61, v61, v61 row_mirror row_mask:0xf bank_mask:0xf
	s_nop 0
	v_add_f32_dpp v60, v60, v60 row_bcast:15 row_mask:0xa bank_mask:0xf
	v_add_f32_dpp v61, v61, v61 row_bcast:15 row_mask:0xa bank_mask:0xf
	s_nop 0
	v_add_f32_dpp v60, v60, v60 row_bcast:31 row_mask:0xc bank_mask:0xf
	v_add_f32_dpp v61, v61, v61 row_bcast:31 row_mask:0xc bank_mask:0xf
	s_nop 0
	v_fma_f32 v60, v60, s22, v64
	v_fma_f32 v61, v61, s22, v64
	v_rsq_f32_e32 v60, v60
	v_rsq_f32_e32 v61, v61
	s_nop 0
	v_readlane_b32 s10, v60, 63
	v_readlane_b32 s11, v61, 63
	s_nop 1
	v_mul_f32_e32 v62, s10, v162
	v_fma_f32 v162, v62, v228, v36
	v_mul_f32_e32 v63, s10, v163
	v_fma_f32 v163, v63, v229, v37
	v_mul_f32_e32 v62, s10, v164
	v_fma_f32 v164, v62, v230, v38
	v_mul_f32_e32 v63, s10, v165
	v_fma_f32 v165, v63, v231, v39
	v_mul_f32_e32 v62, s10, v166
	v_fma_f32 v166, v62, v232, v40
	v_mul_f32_e32 v63, s10, v167
	v_fma_f32 v167, v63, v233, v41
	v_mul_f32_e32 v62, s10, v168
	v_fma_f32 v168, v62, v234, v42
	v_mul_f32_e32 v63, s10, v169
	v_fma_f32 v169, v63, v235, v43
	v_mul_f32_e32 v62, s10, v170
	v_fma_f32 v170, v62, v236, v44
	v_mul_f32_e32 v63, s10, v171
	v_fma_f32 v171, v63, v237, v45
	v_mul_f32_e32 v62, s10, v172
	v_fma_f32 v172, v62, v238, v46
	v_mul_f32_e32 v63, s10, v173
	v_fma_f32 v173, v63, v239, v47
	v_mul_f32_e32 v62, s10, v174
	v_fma_f32 v174, v62, v240, v48
	v_mul_f32_e32 v63, s10, v175
	v_fma_f32 v175, v63, v241, v49
	v_mul_f32_e32 v62, s10, v176
	v_fma_f32 v176, v62, v242, v50
	v_mul_f32_e32 v63, s10, v177
	v_fma_f32 v177, v63, v243, v51
	v_cvt_pk_bf16_f32 v244, v162, v163
	v_cvt_pk_bf16_f32 v245, v164, v165
	v_cvt_pk_bf16_f32 v246, v166, v167
	v_cvt_pk_bf16_f32 v247, v168, v169
	v_cvt_pk_bf16_f32 v248, v170, v171
	v_cvt_pk_bf16_f32 v249, v172, v173
	v_cvt_pk_bf16_f32 v250, v174, v175
	v_cvt_pk_bf16_f32 v251, v176, v177
	global_store_dwordx2 v28, v[244:245], s[2:3]
	global_store_dwordx2 v28, v[246:247], s[2:3] offset:512
	global_store_dwordx2 v28, v[248:249], s[2:3] offset:1024
	global_store_dwordx2 v28, v[250:251], s[2:3] offset:1536
	s_add_u32 s2, s2, 0x60000
	s_addc_u32 s3, s3, 0
	v_mul_f32_e32 v62, s11, v178
	v_fma_f32 v178, v62, v228, v36
	v_mul_f32_e32 v63, s11, v179
	v_fma_f32 v179, v63, v229, v37
	v_mul_f32_e32 v62, s11, v180
	v_fma_f32 v180, v62, v230, v38
	v_mul_f32_e32 v63, s11, v181
	v_fma_f32 v181, v63, v231, v39
	v_mul_f32_e32 v62, s11, v182
	v_fma_f32 v182, v62, v232, v40
	v_mul_f32_e32 v63, s11, v183
	v_fma_f32 v183, v63, v233, v41
	v_mul_f32_e32 v62, s11, v184
	v_fma_f32 v184, v62, v234, v42
	v_mul_f32_e32 v63, s11, v185
	v_fma_f32 v185, v63, v235, v43
	v_mul_f32_e32 v62, s11, v186
	v_fma_f32 v186, v62, v236, v44
	v_mul_f32_e32 v63, s11, v187
	v_fma_f32 v187, v63, v237, v45
	v_mul_f32_e32 v62, s11, v188
	v_fma_f32 v188, v62, v238, v46
	v_mul_f32_e32 v63, s11, v189
	v_fma_f32 v189, v63, v239, v47
	v_mul_f32_e32 v62, s11, v190
	v_fma_f32 v190, v62, v240, v48
	v_mul_f32_e32 v63, s11, v191
	v_fma_f32 v191, v63, v241, v49
	v_mul_f32_e32 v62, s11, v192
	v_fma_f32 v192, v62, v242, v50
	v_mul_f32_e32 v63, s11, v193
	v_fma_f32 v193, v63, v243, v51
	v_cvt_pk_bf16_f32 v10, v178, v179
	v_cvt_pk_bf16_f32 v11, v180, v181
	v_cvt_pk_bf16_f32 v12, v182, v183
	v_cvt_pk_bf16_f32 v13, v184, v185
	v_cvt_pk_bf16_f32 v14, v186, v187
	v_cvt_pk_bf16_f32 v15, v188, v189
	v_cvt_pk_bf16_f32 v16, v190, v191
	v_cvt_pk_bf16_f32 v17, v192, v193
	global_store_dwordx2 v28, v[10:11], s[2:3]
	global_store_dwordx2 v28, v[12:13], s[2:3] offset:512
	global_store_dwordx2 v28, v[14:15], s[2:3] offset:1024
	global_store_dwordx2 v28, v[16:17], s[2:3] offset:1536
	s_add_u32 s2, s2, 0x60000
	s_addc_u32 s3, s3, 0
	s_waitcnt vmcnt(24)
	v_mul_f32_e32 v52, v98, v98
	v_mul_f32_e32 v53, v102, v102
	v_mul_f32_e32 v54, v106, v106
	v_mul_f32_e32 v55, v110, v110
	v_mul_f32_e32 v56, v114, v114
	v_mul_f32_e32 v57, v118, v118
	v_mul_f32_e32 v58, v122, v122
	v_mul_f32_e32 v59, v126, v126
	v_fmac_f32_e32 v52, v99, v99
	v_fmac_f32_e32 v53, v103, v103
	v_fmac_f32_e32 v54, v107, v107
	v_fmac_f32_e32 v55, v111, v111
	v_fmac_f32_e32 v56, v115, v115
	v_fmac_f32_e32 v57, v119, v119
	v_fmac_f32_e32 v58, v123, v123
	v_fmac_f32_e32 v59, v127, v127
	v_fmac_f32_e32 v52, v100, v100
	v_fmac_f32_e32 v53, v104, v104
	v_fmac_f32_e32 v54, v108, v108
	v_fmac_f32_e32 v55, v112, v112
	v_fmac_f32_e32 v56, v116, v116
	v_fmac_f32_e32 v57, v120, v120
	v_fmac_f32_e32 v58, v124, v124
	v_fmac_f32_e32 v59, v128, v128
	v_fmac_f32_e32 v52, v101, v101
	v_fmac_f32_e32 v53, v105, v105
	v_fmac_f32_e32 v54, v109, v109
	v_fmac_f32_e32 v55, v113, v113
	v_fmac_f32_e32 v56, v117, v117
	v_fmac_f32_e32 v57, v121, v121
	v_fmac_f32_e32 v58, v125, v125
	v_fmac_f32_e32 v59, v129, v129
	v_add_f32_e32 v52, v52, v53
	v_add_f32_e32 v54, v54, v55
	v_add_f32_e32 v56, v56, v57
	v_add_f32_e32 v58, v58, v59
	v_add_f32_e32 v60, v52, v54
	v_add_f32_e32 v61, v56, v58
	s_nop 0
	v_add_f32_dpp v60, v60, v60 quad_perm:[1,0,3,2] row_mask:0xf bank_mask:0xf
	v_add_f32_dpp v61, v61, v61 quad_perm:[1,0,3,2] row_mask:0xf bank_mask:0xf
	s_nop 0
	v_add_f32_dpp v60, v60, v60 quad_perm:[2,3,0,1] row_mask:0xf bank_mask:0xf
	v_add_f32_dpp v61, v61, v61 quad_perm:[2,3,0,1] row_mask:0xf bank_mask:0xf
	s_nop 0
	v_add_f32_dpp v60, v60, v60 row_half_mirror row_mask:0xf bank_mask:0xf
	v_add_f32_dpp v61, v61, v61 row_half_mirror row_mask:0xf bank_mask:0xf
	s_nop 0
	v_add_f32_dpp v60, v60, v60 row_mirror row_mask:0xf bank_mask:0xf
	v_add_f32_dpp v61, v61, v61 row_mirror row_mask:0xf bank_mask:0xf
	s_nop 0
	v_add_f32_dpp v60, v60, v60 row_bcast:15 row_mask:0xa bank_mask:0xf
	v_add_f32_dpp v61, v61, v61 row_bcast:15 row_mask:0xa bank_mask:0xf
	s_nop 0
	v_add_f32_dpp v60, v60, v60 row_bcast:31 row_mask:0xc bank_mask:0xf
	v_add_f32_dpp v61, v61, v61 row_bcast:31 row_mask:0xc bank_mask:0xf
	s_nop 0
	v_fma_f32 v60, v60, s22, v64
	v_fma_f32 v61, v61, s22, v64
	v_rsq_f32_e32 v60, v60
	v_rsq_f32_e32 v61, v61
	s_nop 0
	v_readlane_b32 s10, v60, 63
	v_readlane_b32 s11, v61, 63
	s_nop 1
	v_mul_f32_e32 v62, s10, v98
	v_fma_f32 v98, v62, v228, v36
	v_mul_f32_e32 v63, s10, v99
	v_fma_f32 v99, v63, v229, v37
	v_mul_f32_e32 v62, s10, v100
	v_fma_f32 v100, v62, v230, v38
	v_mul_f32_e32 v63, s10, v101
	v_fma_f32 v101, v63, v231, v39
	v_mul_f32_e32 v62, s10, v102
	v_fma_f32 v102, v62, v232, v40
	v_mul_f32_e32 v63, s10, v103
	v_fma_f32 v103, v63, v233, v41
	v_mul_f32_e32 v62, s10, v104
	v_fma_f32 v104, v62, v234, v42
	v_mul_f32_e32 v63, s10, v105
	v_fma_f32 v105, v63, v235, v43
	v_mul_f32_e32 v62, s10, v106
	v_fma_f32 v106, v62, v236, v44
	v_mul_f32_e32 v63, s10, v107
	v_fma_f32 v107, v63, v237, v45
	v_mul_f32_e32 v62, s10, v108
	v_fma_f32 v108, v62, v238, v46
	v_mul_f32_e32 v63, s10, v109
	v_fma_f32 v109, v63, v239, v47
	v_mul_f32_e32 v62, s10, v110
	v_fma_f32 v110, v62, v240, v48
	v_mul_f32_e32 v63, s10, v111
	v_fma_f32 v111, v63, v241, v49
	v_mul_f32_e32 v62, s10, v112
	v_fma_f32 v112, v62, v242, v50
	v_mul_f32_e32 v63, s10, v113
	v_fma_f32 v113, v63, v243, v51
	v_cvt_pk_bf16_f32 v244, v98, v99
	v_cvt_pk_bf16_f32 v245, v100, v101
	v_cvt_pk_bf16_f32 v246, v102, v103
	v_cvt_pk_bf16_f32 v247, v104, v105
	v_cvt_pk_bf16_f32 v248, v106, v107
	v_cvt_pk_bf16_f32 v249, v108, v109
	v_cvt_pk_bf16_f32 v250, v110, v111
	v_cvt_pk_bf16_f32 v251, v112, v113
	global_store_dwordx2 v28, v[244:245], s[2:3]
	global_store_dwordx2 v28, v[246:247], s[2:3] offset:512
	global_store_dwordx2 v28, v[248:249], s[2:3] offset:1024
	global_store_dwordx2 v28, v[250:251], s[2:3] offset:1536
	s_add_u32 s2, s2, 0x60000
	s_addc_u32 s3, s3, 0
	v_mul_f32_e32 v62, s11, v114
	v_fma_f32 v114, v62, v228, v36
	v_mul_f32_e32 v63, s11, v115
	v_fma_f32 v115, v63, v229, v37
	v_mul_f32_e32 v62, s11, v116
	v_fma_f32 v116, v62, v230, v38
	v_mul_f32_e32 v63, s11, v117
	v_fma_f32 v117, v63, v231, v39
	v_mul_f32_e32 v62, s11, v118
	v_fma_f32 v118, v62, v232, v40
	v_mul_f32_e32 v63, s11, v119
	v_fma_f32 v119, v63, v233, v41
	v_mul_f32_e32 v62, s11, v120
	v_fma_f32 v120, v62, v234, v42
	v_mul_f32_e32 v63, s11, v121
	v_fma_f32 v121, v63, v235, v43
	v_mul_f32_e32 v62, s11, v122
	v_fma_f32 v122, v62, v236, v44
	v_mul_f32_e32 v63, s11, v123
	v_fma_f32 v123, v63, v237, v45
	v_mul_f32_e32 v62, s11, v124
	v_fma_f32 v124, v62, v238, v46
	v_mul_f32_e32 v63, s11, v125
	v_fma_f32 v125, v63, v239, v47
	v_mul_f32_e32 v62, s11, v126
	v_fma_f32 v126, v62, v240, v48
	v_mul_f32_e32 v63, s11, v127
	v_fma_f32 v127, v63, v241, v49
	v_mul_f32_e32 v62, s11, v128
	v_fma_f32 v128, v62, v242, v50
	v_mul_f32_e32 v63, s11, v129
	v_fma_f32 v129, v63, v243, v51
	v_cvt_pk_bf16_f32 v10, v114, v115
	v_cvt_pk_bf16_f32 v11, v116, v117
	v_cvt_pk_bf16_f32 v12, v118, v119
	v_cvt_pk_bf16_f32 v13, v120, v121
	v_cvt_pk_bf16_f32 v14, v122, v123
	v_cvt_pk_bf16_f32 v15, v124, v125
	v_cvt_pk_bf16_f32 v16, v126, v127
	v_cvt_pk_bf16_f32 v17, v128, v129
	global_store_dwordx2 v28, v[10:11], s[2:3]
	global_store_dwordx2 v28, v[12:13], s[2:3] offset:512
	global_store_dwordx2 v28, v[14:15], s[2:3] offset:1024
	global_store_dwordx2 v28, v[16:17], s[2:3] offset:1536
	s_add_u32 s2, s2, 0x60000
	s_addc_u32 s3, s3, 0
	s_waitcnt vmcnt(16)
	v_mul_f32_e32 v52, v130, v130
	v_mul_f32_e32 v53, v134, v134
	v_mul_f32_e32 v54, v138, v138
	v_mul_f32_e32 v55, v142, v142
	v_mul_f32_e32 v56, v146, v146
	v_mul_f32_e32 v57, v150, v150
	v_mul_f32_e32 v58, v154, v154
	v_mul_f32_e32 v59, v158, v158
	v_fmac_f32_e32 v52, v131, v131
	v_fmac_f32_e32 v53, v135, v135
	v_fmac_f32_e32 v54, v139, v139
	v_fmac_f32_e32 v55, v143, v143
	v_fmac_f32_e32 v56, v147, v147
	v_fmac_f32_e32 v57, v151, v151
	v_fmac_f32_e32 v58, v155, v155
	v_fmac_f32_e32 v59, v159, v159
	v_fmac_f32_e32 v52, v132, v132
	v_fmac_f32_e32 v53, v136, v136
	v_fmac_f32_e32 v54, v140, v140
	v_fmac_f32_e32 v55, v144, v144
	v_fmac_f32_e32 v56, v148, v148
	v_fmac_f32_e32 v57, v152, v152
	v_fmac_f32_e32 v58, v156, v156
	v_fmac_f32_e32 v59, v160, v160
	v_fmac_f32_e32 v52, v133, v133
	v_fmac_f32_e32 v53, v137, v137
	v_fmac_f32_e32 v54, v141, v141
	v_fmac_f32_e32 v55, v145, v145
	v_fmac_f32_e32 v56, v149, v149
	v_fmac_f32_e32 v57, v153, v153
	v_fmac_f32_e32 v58, v157, v157
	v_fmac_f32_e32 v59, v161, v161
	v_add_f32_e32 v52, v52, v53
	v_add_f32_e32 v54, v54, v55
	v_add_f32_e32 v56, v56, v57
	v_add_f32_e32 v58, v58, v59
	v_add_f32_e32 v60, v52, v54
	v_add_f32_e32 v61, v56, v58
	s_nop 0
	v_add_f32_dpp v60, v60, v60 quad_perm:[1,0,3,2] row_mask:0xf bank_mask:0xf
	v_add_f32_dpp v61, v61, v61 quad_perm:[1,0,3,2] row_mask:0xf bank_mask:0xf
	s_nop 0
	v_add_f32_dpp v60, v60, v60 quad_perm:[2,3,0,1] row_mask:0xf bank_mask:0xf
	v_add_f32_dpp v61, v61, v61 quad_perm:[2,3,0,1] row_mask:0xf bank_mask:0xf
	s_nop 0
	v_add_f32_dpp v60, v60, v60 row_half_mirror row_mask:0xf bank_mask:0xf
	v_add_f32_dpp v61, v61, v61 row_half_mirror row_mask:0xf bank_mask:0xf
	s_nop 0
	v_add_f32_dpp v60, v60, v60 row_mirror row_mask:0xf bank_mask:0xf
	v_add_f32_dpp v61, v61, v61 row_mirror row_mask:0xf bank_mask:0xf
	s_nop 0
	v_add_f32_dpp v60, v60, v60 row_bcast:15 row_mask:0xa bank_mask:0xf
	v_add_f32_dpp v61, v61, v61 row_bcast:15 row_mask:0xa bank_mask:0xf
	s_nop 0
	v_add_f32_dpp v60, v60, v60 row_bcast:31 row_mask:0xc bank_mask:0xf
	v_add_f32_dpp v61, v61, v61 row_bcast:31 row_mask:0xc bank_mask:0xf
	s_nop 0
	v_fma_f32 v60, v60, s22, v64
	v_fma_f32 v61, v61, s22, v64
	v_rsq_f32_e32 v60, v60
	v_rsq_f32_e32 v61, v61
	s_nop 0
	v_readlane_b32 s10, v60, 63
	v_readlane_b32 s11, v61, 63
	s_nop 1
	v_mul_f32_e32 v62, s10, v130
	v_fma_f32 v130, v62, v228, v36
	v_mul_f32_e32 v63, s10, v131
	v_fma_f32 v131, v63, v229, v37
	v_mul_f32_e32 v62, s10, v132
	v_fma_f32 v132, v62, v230, v38
	v_mul_f32_e32 v63, s10, v133
	v_fma_f32 v133, v63, v231, v39
	v_mul_f32_e32 v62, s10, v134
	v_fma_f32 v134, v62, v232, v40
	v_mul_f32_e32 v63, s10, v135
	v_fma_f32 v135, v63, v233, v41
	v_mul_f32_e32 v62, s10, v136
	v_fma_f32 v136, v62, v234, v42
	v_mul_f32_e32 v63, s10, v137
	v_fma_f32 v137, v63, v235, v43
	v_mul_f32_e32 v62, s10, v138
	v_fma_f32 v138, v62, v236, v44
	v_mul_f32_e32 v63, s10, v139
	v_fma_f32 v139, v63, v237, v45
	v_mul_f32_e32 v62, s10, v140
	v_fma_f32 v140, v62, v238, v46
	v_mul_f32_e32 v63, s10, v141
	v_fma_f32 v141, v63, v239, v47
	v_mul_f32_e32 v62, s10, v142
	v_fma_f32 v142, v62, v240, v48
	v_mul_f32_e32 v63, s10, v143
	v_fma_f32 v143, v63, v241, v49
	v_mul_f32_e32 v62, s10, v144
	v_fma_f32 v144, v62, v242, v50
	v_mul_f32_e32 v63, s10, v145
	v_fma_f32 v145, v63, v243, v51
	v_cvt_pk_bf16_f32 v244, v130, v131
	v_cvt_pk_bf16_f32 v245, v132, v133
	v_cvt_pk_bf16_f32 v246, v134, v135
	v_cvt_pk_bf16_f32 v247, v136, v137
	v_cvt_pk_bf16_f32 v248, v138, v139
	v_cvt_pk_bf16_f32 v249, v140, v141
	v_cvt_pk_bf16_f32 v250, v142, v143
	v_cvt_pk_bf16_f32 v251, v144, v145
	global_store_dwordx2 v28, v[244:245], s[2:3]
	global_store_dwordx2 v28, v[246:247], s[2:3] offset:512
	global_store_dwordx2 v28, v[248:249], s[2:3] offset:1024
	global_store_dwordx2 v28, v[250:251], s[2:3] offset:1536
	s_add_u32 s2, s2, s28
	s_addc_u32 s3, s3, 0
	v_mul_f32_e32 v62, s11, v146
	v_fma_f32 v146, v62, v228, v36
	v_mul_f32_e32 v63, s11, v147
	v_fma_f32 v147, v63, v229, v37
	v_mul_f32_e32 v62, s11, v148
	v_fma_f32 v148, v62, v230, v38
	v_mul_f32_e32 v63, s11, v149
	v_fma_f32 v149, v63, v231, v39
	v_mul_f32_e32 v62, s11, v150
	v_fma_f32 v150, v62, v232, v40
	v_mul_f32_e32 v63, s11, v151
	v_fma_f32 v151, v63, v233, v41
	v_mul_f32_e32 v62, s11, v152
	v_fma_f32 v152, v62, v234, v42
	v_mul_f32_e32 v63, s11, v153
	v_fma_f32 v153, v63, v235, v43
	v_mul_f32_e32 v62, s11, v154
	v_fma_f32 v154, v62, v236, v44
	v_mul_f32_e32 v63, s11, v155
	v_fma_f32 v155, v63, v237, v45
	v_mul_f32_e32 v62, s11, v156
	v_fma_f32 v156, v62, v238, v46
	v_mul_f32_e32 v63, s11, v157
	v_fma_f32 v157, v63, v239, v47
	v_mul_f32_e32 v62, s11, v158
	v_fma_f32 v158, v62, v240, v48
	v_mul_f32_e32 v63, s11, v159
	v_fma_f32 v159, v63, v241, v49
	v_mul_f32_e32 v62, s11, v160
	v_fma_f32 v160, v62, v242, v50
	v_mul_f32_e32 v63, s11, v161
	v_fma_f32 v161, v63, v243, v51
	v_cvt_pk_bf16_f32 v10, v146, v147
	v_cvt_pk_bf16_f32 v11, v148, v149
	v_cvt_pk_bf16_f32 v12, v150, v151
	v_cvt_pk_bf16_f32 v13, v152, v153
	v_cvt_pk_bf16_f32 v14, v154, v155
	v_cvt_pk_bf16_f32 v15, v156, v157
	v_cvt_pk_bf16_f32 v16, v158, v159
	v_cvt_pk_bf16_f32 v17, v160, v161
	global_store_dwordx2 v28, v[10:11], s[2:3]
	global_store_dwordx2 v28, v[12:13], s[2:3] offset:512
	global_store_dwordx2 v28, v[14:15], s[2:3] offset:1024
	global_store_dwordx2 v28, v[16:17], s[2:3] offset:1536
	s_branch .LBB0_443
